# GEMM K-loops: the loop head's LDS-offset arithmetic also moved in front of the per-K-tile barrier (one copy at loop entry, one in the latch); the head starts at the fragment reads
# baseline (speedup 1.0000x reference)
.LBB0_828:
	s_mul_i32 s6, s38, 0xfffffefc
	s_add_i32 s6, s6, s55
	s_ashr_i32 s10, s6, 2
	s_lshl_b32 s7, s55, 8
	s_mul_i32 s1, s1, 0x220000
	s_mul_hi_u32 s11, s0, 0x220000
	s_lshl_b32 s6, s10, 8
	s_and_b32 s7, s7, 0x300
	s_add_i32 s11, s11, s1
	s_mul_i32 s0, s0, 0x220000
	s_add_u32 s12, s84, s0
	s_addc_u32 s13, s85, s11
	v_mov_b32_e32 v1, v174
	s_cmp_lg_u32 s10, 64
	s_cselect_b64 s[0:1], -1, 0
	v_readfirstlane_b32 s11, v1
	s_ashr_i32 s34, s11, 6
	s_waitcnt vmcnt(0)
	v_bfe_u32 v6, v1, 2, 4
	s_lshl_b32 s18, s34, 4
	v_or_b32_e32 v4, s6, v6
	s_add_i32 s19, s18, 0x80
	v_add_u32_e32 v2, s18, v4
	v_add_u32_e32 v4, s19, v4
	v_ashrrev_i32_e32 v3, 31, v2
	v_ashrrev_i32_e32 v5, 31, v4
	s_and_b32 s10, s34, 3
	v_lshlrev_b64 v[2:3], 11, v[2:3]
	v_lshlrev_b64 v[4:5], 11, v[4:5]
	s_waitcnt vmcnt(16)
	v_or_b32_e32 v11, s7, v6
	s_ashr_i32 s11, s11, 8
	v_lshl_add_u64 v[4:5], s[4:5], 0, v[4:5]
	v_add_u32_e32 v8, s18, v11
	v_mov_b64_e32 v[6:7], s[12:13]
	v_add_u32_e32 v11, s19, v11
	v_lshl_add_u64 v[2:3], s[4:5], 0, v[2:3]
	s_lshl_b32 s4, s11, 13
	s_lshl_b32 s5, s10, 12
	v_bfe_u32 v171, v1, 4, 2
	v_mad_i64_i32 v[8:9], s[12:13], v8, s52, v[6:7]
	v_mad_i64_i32 v[6:7], s[12:13], v11, s52, v[6:7]
	s_cmp_lg_u32 s11, 1
	v_bitop3_b32 v10, v171, v1, 3 bitop3:0x78
	s_cselect_b64 s[18:19], -1, 0
	s_lshl_b32 s13, s34, 10
	v_lshlrev_b32_e32 v10, 4, v10
	v_mov_b32_e32 v11, v0
	s_add_i32 s12, s13, 0
	v_lshl_add_u64 v[160:161], v[2:3], 0, v[10:11]
	s_mov_b32 m0, s12
	v_lshl_add_u64 v[162:163], v[4:5], 0, v[10:11]
	global_load_lds_dwordx4 v[160:161], off
	s_add_i32 m0, s12, 0x2000
	v_lshl_add_u64 v[164:165], v[8:9], 0, v[10:11]
	global_load_lds_dwordx4 v[162:163], off
	s_add_i32 m0, s12, 0x4000
	v_lshl_add_u64 v[166:167], v[6:7], 0, v[10:11]
	global_load_lds_dwordx4 v[164:165], off
	s_add_i32 m0, s12, 0x6000
	v_lshl_add_u64 v[2:3], v[160:161], 0, 64
	global_load_lds_dwordx4 v[166:167], off
	s_add_i32 m0, s12, 0x8000
	s_add_i32 s34, s13, 0x2000
	global_load_lds_dwordx4 v[2:3], off
	v_lshl_add_u64 v[2:3], v[162:163], 0, 64
	s_add_i32 m0, s12, 0xa000
	v_and_b32_e32 v172, 15, v1
	global_load_lds_dwordx4 v[2:3], off
	v_lshl_add_u64 v[2:3], v[164:165], 0, 64
	s_add_i32 m0, s12, 0xc000
	v_lshrrev_b32_e32 v1, 2, v1
	global_load_lds_dwordx4 v[2:3], off
	v_lshl_add_u64 v[2:3], v[166:167], 0, 64
	s_add_i32 m0, s12, 0xe000
	v_bitop3_b32 v1, v171, v1, 3 bitop3:0x78
	global_load_lds_dwordx4 v[2:3], off
	v_lshl_add_u64 v[2:3], v[160:161], 0, s[42:43]
	s_add_i32 m0, s53, s13
	v_lshlrev_b32_e32 v173, 4, v1
	global_load_lds_dwordx4 v[2:3], off
	v_lshl_add_u64 v[2:3], v[162:163], 0, s[42:43]
	s_add_i32 m0, s53, s34
	v_mov_b32_e32 v1, v0
	global_load_lds_dwordx4 v[2:3], off
	v_lshl_add_u64 v[2:3], v[164:165], 0, s[42:43]
	s_add_i32 m0, s54, s13
	v_lshlrev_b32_e32 v176, 6, v172
	global_load_lds_dwordx4 v[2:3], off
	v_lshl_add_u64 v[2:3], v[166:167], 0, s[42:43]
	s_add_i32 m0, s54, s34
	s_or_b64 s[0:1], s[0:1], s[18:19]
	global_load_lds_dwordx4 v[2:3], off
	s_waitcnt vmcnt(8)
	v_mov_b32_e32 v2, v0
	v_mov_b32_e32 v3, v0
	s_waitcnt lgkmcnt(0)
	s_barrier
	s_waitcnt vmcnt(0)
	v_mov_b64_e32 v[16:17], v[2:3]
	v_mov_b64_e32 v[24:25], v[2:3]
	v_mov_b64_e32 v[28:29], v[2:3]
	v_mov_b64_e32 v[32:33], v[2:3]
	v_mov_b64_e32 v[36:37], v[2:3]
	v_mov_b64_e32 v[40:41], v[2:3]
	v_mov_b64_e32 v[44:45], v[2:3]
	v_mov_b64_e32 v[48:49], v[2:3]
	v_mov_b64_e32 v[52:53], v[2:3]
	v_mov_b64_e32 v[56:57], v[2:3]
	v_mov_b64_e32 v[60:61], v[2:3]
	v_mov_b64_e32 v[64:65], v[2:3]
	v_mov_b64_e32 v[68:69], v[2:3]
	v_mov_b64_e32 v[72:73], v[2:3]
	v_mov_b64_e32 v[76:77], v[2:3]
	v_mov_b64_e32 v[80:81], v[2:3]
	v_mov_b64_e32 v[84:85], v[2:3]
	v_mov_b64_e32 v[88:89], v[2:3]
	v_mov_b64_e32 v[92:93], v[2:3]
	v_mov_b64_e32 v[96:97], v[2:3]
	v_mov_b64_e32 v[100:101], v[2:3]
	v_mov_b64_e32 v[104:105], v[2:3]
	v_mov_b64_e32 v[108:109], v[2:3]
	v_mov_b64_e32 v[112:113], v[2:3]
	v_mov_b64_e32 v[116:117], v[2:3]
	v_mov_b64_e32 v[120:121], v[2:3]
	v_mov_b64_e32 v[124:125], v[2:3]
	v_mov_b64_e32 v[128:129], v[2:3]
	v_mov_b64_e32 v[20:21], v[2:3]
	v_mov_b64_e32 v[12:13], v[2:3]
	v_mov_b64_e32 v[8:9], v[2:3]
	v_mov_b64_e32 v[14:15], v[0:1]
	v_mov_b64_e32 v[22:23], v[0:1]
	v_mov_b64_e32 v[26:27], v[0:1]
	v_mov_b64_e32 v[30:31], v[0:1]
	v_mov_b64_e32 v[34:35], v[0:1]
	v_mov_b64_e32 v[38:39], v[0:1]
	v_mov_b64_e32 v[42:43], v[0:1]
	v_mov_b64_e32 v[46:47], v[0:1]
	v_mov_b64_e32 v[50:51], v[0:1]
	v_mov_b64_e32 v[54:55], v[0:1]
	v_mov_b64_e32 v[58:59], v[0:1]
	v_mov_b64_e32 v[62:63], v[0:1]
	v_mov_b64_e32 v[66:67], v[0:1]
	v_mov_b64_e32 v[70:71], v[0:1]
	v_mov_b64_e32 v[74:75], v[0:1]
	v_mov_b64_e32 v[78:79], v[0:1]
	v_mov_b64_e32 v[82:83], v[0:1]
	v_mov_b64_e32 v[86:87], v[0:1]
	v_mov_b64_e32 v[90:91], v[0:1]
	v_mov_b64_e32 v[94:95], v[0:1]
	v_mov_b64_e32 v[98:99], v[0:1]
	v_mov_b64_e32 v[102:103], v[0:1]
	v_mov_b64_e32 v[106:107], v[0:1]
	v_mov_b64_e32 v[110:111], v[0:1]
	v_mov_b64_e32 v[114:115], v[0:1]
	v_mov_b64_e32 v[118:119], v[0:1]
	v_mov_b64_e32 v[122:123], v[0:1]
	v_mov_b64_e32 v[126:127], v[0:1]
	v_mov_b64_e32 v[18:19], v[0:1]
	v_mov_b64_e32 v[10:11], v[0:1]
	v_mov_b64_e32 v[6:7], v[0:1]
	v_mov_b64_e32 v[4:5], v[2:3]
	s_movk_i32 s13, 0x60
	s_mov_b32 s18, 0
	v_mov_b64_e32 v[2:3], v[0:1]
	s_mov_b32 s19, 0
	s_and_b32 s34, s18, 0x18000
	s_add_i32 s34, s34, 0
	s_add_i32 s35, s34, s5
	v_add3_u32 v1, s35, v176, v173
	s_add_i32 s34, s34, s4
	s_branch .LBB0_830

.Lnd0_wd:
	s_add_i32 s19, s19, 1
	s_add_i32 s13, s13, 32
	s_add_i32 s18, s18, 0x8000
	s_and_b32 s34, s18, 0x18000
	s_add_i32 s34, s34, 0
	s_add_i32 s35, s34, s5
	v_add3_u32 v1, s35, v176, v173
	s_add_i32 s34, s34, s4
	s_cmpk_eq_i32 s13, 0x460
	s_waitcnt lgkmcnt(0)
	s_barrier
	s_cbranch_scc1 .LBB0_832
.LBB0_830:
	s_waitcnt lgkmcnt(0)
	ds_read_b128 v[130:133], v1 offset:16384
	ds_read_b128 v[134:137], v1 offset:17408
	ds_read_b128 v[138:141], v1 offset:18432
	ds_read_b128 v[142:145], v1 offset:19456
	v_add_u32_e32 v1, s34, v176
	s_add_i32 s34, s18, 0x18000
	s_and_b32 s44, s34, 0x18000
	s_cmp_lt_u32 s19, 29
	s_cselect_b32 s38, s13, 0x3e0
	s_lshl_b64 s[34:35], s[38:39], 1
	s_add_i32 s44, s12, s44
	v_add_u32_e32 v1, v1, v173
	ds_read_b128 v[154:157], v1
	ds_read_b128 v[150:153], v1 offset:1024
	ds_read_b128 v[146:149], v1 offset:2048
	s_andn2_b64 vcc, exec, s[0:1]
	s_cmp_lt_u32 s19, 29
	s_cbranch_scc0 .Lnd0_skip
	s_mov_b32 m0, s44
	v_lshl_add_u64 v[194:195], v[160:161], 0, s[34:35]
	global_load_lds_dwordx4 v[194:195], off
	s_add_i32 m0, s44, 0x2000
	v_lshl_add_u64 v[194:195], v[162:163], 0, s[34:35]
	global_load_lds_dwordx4 v[194:195], off
	s_add_i32 m0, s44, 0x4000
	v_lshl_add_u64 v[194:195], v[164:165], 0, s[34:35]
	global_load_lds_dwordx4 v[194:195], off
	s_add_i32 m0, s44, 0x6000
	v_lshl_add_u64 v[194:195], v[166:167], 0, s[34:35]
	global_load_lds_dwordx4 v[194:195], off

.LBB0_1328:
	s_and_b32 vcc_lo, s21, 7
	s_lshl_b32 vcc_lo, vcc_lo, 5
	s_lshr_b32 vcc_hi, s21, 3
	s_or_b32 vcc_lo, vcc_lo, vcc_hi
	s_cmpk_lt_i32 s21, 0x100
	s_cselect_b32 vcc_lo, vcc_lo, s21
	s_cmpk_lt_i32 s21, 0x100
	s_cselect_b64 s[10:11], -1, 0
	s_lshl_b32 s1, vcc_lo, 8
	s_and_b32 s12, s1, 0x300
	s_lshl_b32 s1, s21, 4
	s_lshl_b32 s0, vcc_lo, 6
	s_andn2_b32 s1, s1, 63
	s_and_b32 s0, s0, 0xffffff00
	s_addk_i32 s1, 0xf000
	s_cmpk_gt_i32 s21, 0xff
	s_cselect_b32 s22, 0x4000, s0
	s_cselect_b32 s0, s1, 0
	s_cselect_b32 s13, 2, 32
	s_cselect_b32 s8, 64, 0x80
	s_ashr_i32 s1, s0, 31
	s_lshl_b64 s[0:1], s[0:1], 1
	s_add_u32 s24, s88, s0
	s_waitcnt vmcnt(1)
	v_mov_b32_e32 v10, v174
	s_addc_u32 s25, s89, s1
	s_add_u32 s0, s28, s0
	v_readfirstlane_b32 s15, v10
	s_addc_u32 s1, s29, s1
	s_ashr_i32 s23, s15, 6
	v_bfe_u32 v0, v10, 2, 4
	s_lshl_b32 s26, s23, 4
	v_or_b32_e32 v2, s22, v0
	s_add_i32 s27, s26, 0x80
	v_or_b32_e32 v0, s12, v0
	s_and_b32 s14, s23, 3
	v_add_u32_e32 v12, s26, v2
	v_add_u32_e32 v4, s27, v2
	v_mov_b64_e32 v[2:3], s[24:25]
	s_waitcnt vmcnt(0)
	v_add_u32_e32 v8, s26, v0
	v_mov_b64_e32 v[6:7], s[0:1]
	v_add_u32_e32 v0, s27, v0
	s_ashr_i32 s15, s15, 8
	v_bfe_u32 v166, v10, 4, 2
	v_mad_i64_i32 v[4:5], s[24:25], v4, s16, v[2:3]
	v_mad_i64_i32 v[8:9], s[0:1], v8, s16, v[6:7]
	v_mad_i64_i32 v[6:7], s[0:1], v0, s16, v[6:7]
	v_mad_i64_i32 v[2:3], s[0:1], v12, s16, v[2:3]
	s_cmp_lg_u32 s15, 1
	v_bitop3_b32 v11, v166, v10, 3 bitop3:0x78
	s_cselect_b64 s[0:1], -1, 0
	s_lshl_b32 s24, s23, 10
	v_lshlrev_b32_e32 v0, 4, v11
	s_add_i32 s23, s24, 0
	v_lshl_add_u64 v[158:159], v[2:3], 0, v[0:1]
	s_mov_b32 m0, s23
	v_lshl_add_u64 v[160:161], v[4:5], 0, v[0:1]
	global_load_lds_dwordx4 v[158:159], off
	s_add_i32 m0, s23, 0x2000
	v_lshl_add_u64 v[162:163], v[8:9], 0, v[0:1]
	global_load_lds_dwordx4 v[160:161], off
	s_add_i32 m0, s23, 0x4000
	v_lshl_add_u64 v[164:165], v[6:7], 0, v[0:1]
	global_load_lds_dwordx4 v[162:163], off
	s_add_i32 m0, s23, 0x6000
	v_lshl_add_u64 v[2:3], v[158:159], 0, 64
	global_load_lds_dwordx4 v[164:165], off
	s_add_i32 m0, s23, 0x8000
	s_add_i32 s25, s24, 0x2000
	global_load_lds_dwordx4 v[2:3], off
	v_lshl_add_u64 v[2:3], v[160:161], 0, 64
	s_add_i32 m0, s23, 0xa000
	v_lshrrev_b32_e32 v0, 2, v10
	global_load_lds_dwordx4 v[2:3], off
	v_lshl_add_u64 v[2:3], v[162:163], 0, 64
	s_add_i32 m0, s23, 0xc000
	v_bitop3_b32 v0, v166, v0, 3 bitop3:0x78
	global_load_lds_dwordx4 v[2:3], off
	v_lshl_add_u64 v[2:3], v[164:165], 0, 64
	s_add_i32 m0, s23, 0xe000
	s_or_b64 s[0:1], s[10:11], s[0:1]
	global_load_lds_dwordx4 v[2:3], off
	v_lshl_add_u64 v[2:3], v[158:159], 0, s[8:9]
	s_add_i32 m0, s18, s24
	v_and_b32_e32 v167, 15, v10
	global_load_lds_dwordx4 v[2:3], off
	v_lshl_add_u64 v[2:3], v[160:161], 0, s[8:9]
	s_add_i32 m0, s18, s25
	v_lshlrev_b32_e32 v169, 4, v0
	global_load_lds_dwordx4 v[2:3], off
	v_lshl_add_u64 v[2:3], v[162:163], 0, s[8:9]
	s_add_i32 m0, s19, s24
	v_mov_b32_e32 v0, v1
	global_load_lds_dwordx4 v[2:3], off
	v_lshl_add_u64 v[2:3], v[164:165], 0, s[8:9]
	s_add_i32 m0, s19, s25
	v_cndmask_b32_e64 v4, 0, 1, s[0:1]
	global_load_lds_dwordx4 v[2:3], off
	s_waitcnt vmcnt(8)
	v_mov_b32_e32 v2, v1
	v_mov_b32_e32 v3, v1
	s_waitcnt lgkmcnt(0)
	s_barrier
	v_mov_b64_e32 v[20:21], v[2:3]
	v_mov_b64_e32 v[24:25], v[2:3]
	v_mov_b64_e32 v[28:29], v[2:3]
	v_mov_b64_e32 v[32:33], v[2:3]
	v_mov_b64_e32 v[36:37], v[2:3]
	v_mov_b64_e32 v[40:41], v[2:3]
	v_mov_b64_e32 v[44:45], v[2:3]
	s_waitcnt vmcnt(0)
	v_mov_b64_e32 v[48:49], v[2:3]
	v_mov_b64_e32 v[52:53], v[2:3]
	v_mov_b64_e32 v[56:57], v[2:3]
	v_mov_b64_e32 v[60:61], v[2:3]
	v_mov_b64_e32 v[64:65], v[2:3]
	v_mov_b64_e32 v[68:69], v[2:3]
	v_mov_b64_e32 v[72:73], v[2:3]
	v_mov_b64_e32 v[76:77], v[2:3]
	v_mov_b64_e32 v[80:81], v[2:3]
	v_mov_b64_e32 v[84:85], v[2:3]
	v_mov_b64_e32 v[88:89], v[2:3]
	v_mov_b64_e32 v[92:93], v[2:3]
	v_mov_b64_e32 v[96:97], v[2:3]
	v_mov_b64_e32 v[100:101], v[2:3]
	v_mov_b64_e32 v[104:105], v[2:3]
	v_mov_b64_e32 v[108:109], v[2:3]
	v_mov_b64_e32 v[112:113], v[2:3]
	v_mov_b64_e32 v[116:117], v[2:3]
	v_mov_b64_e32 v[120:121], v[2:3]
	v_mov_b64_e32 v[124:125], v[2:3]
	v_mov_b64_e32 v[128:129], v[2:3]
	v_mov_b64_e32 v[16:17], v[2:3]
	v_mov_b64_e32 v[12:13], v[2:3]
	v_mov_b64_e32 v[8:9], v[2:3]
	v_cmp_ne_u32_e64 s[0:1], 1, v4
	v_mov_b64_e32 v[18:19], v[0:1]
	v_mov_b64_e32 v[22:23], v[0:1]
	v_mov_b64_e32 v[26:27], v[0:1]
	v_mov_b64_e32 v[30:31], v[0:1]
	v_mov_b64_e32 v[34:35], v[0:1]
	v_mov_b64_e32 v[38:39], v[0:1]
	v_mov_b64_e32 v[42:43], v[0:1]
	v_mov_b64_e32 v[46:47], v[0:1]
	v_mov_b64_e32 v[50:51], v[0:1]
	v_mov_b64_e32 v[54:55], v[0:1]
	v_mov_b64_e32 v[58:59], v[0:1]
	v_mov_b64_e32 v[62:63], v[0:1]
	v_mov_b64_e32 v[66:67], v[0:1]
	v_mov_b64_e32 v[70:71], v[0:1]
	v_mov_b64_e32 v[74:75], v[0:1]
	v_mov_b64_e32 v[78:79], v[0:1]
	v_mov_b64_e32 v[82:83], v[0:1]
	v_mov_b64_e32 v[86:87], v[0:1]
	v_mov_b64_e32 v[90:91], v[0:1]
	v_mov_b64_e32 v[94:95], v[0:1]
	v_mov_b64_e32 v[98:99], v[0:1]
	v_mov_b64_e32 v[102:103], v[0:1]
	v_mov_b64_e32 v[106:107], v[0:1]
	v_mov_b64_e32 v[110:111], v[0:1]
	v_mov_b64_e32 v[114:115], v[0:1]
	v_mov_b64_e32 v[118:119], v[0:1]
	v_mov_b64_e32 v[122:123], v[0:1]
	v_mov_b64_e32 v[126:127], v[0:1]
	v_mov_b64_e32 v[14:15], v[0:1]
	v_mov_b64_e32 v[10:11], v[0:1]
	v_mov_b64_e32 v[6:7], v[0:1]
	v_mov_b64_e32 v[4:5], v[2:3]
	s_add_i32 s24, s13, -1
	s_lshl_b32 s25, s14, 12
	v_lshlrev_b32_e32 v168, 6, v167
	s_lshl_b32 s26, s15, 13
	s_mov_b32 s27, 0x18000
	v_mov_b64_e32 v[2:3], v[0:1]
	s_mov_b32 s34, s9
	s_add_i32 s8, s27, 0xfffe8000
	s_and_b32 s8, s8, 0x18000
	s_add_i32 s8, s8, 0
	s_add_i32 s35, s8, s25
	v_add3_u32 v0, s35, v168, v169
	s_add_i32 s8, s8, s26
	s_branch .LBB0_1330
.LBB0_1329:
	s_waitcnt vmcnt(8)
	s_add_i32 s34, s34, 1
	s_add_i32 s27, s27, 0x8000
	s_add_i32 s8, s27, 0xfffe8000
	s_and_b32 s8, s8, 0x18000
	s_add_i32 s8, s8, 0
	s_add_i32 s35, s8, s25
	v_add3_u32 v0, s35, v168, v169
	s_add_i32 s8, s8, s26
	s_cmp_eq_u32 s13, s34
	s_waitcnt lgkmcnt(0)
	s_barrier
	s_cbranch_scc1 .LBB0_1332
.LBB0_1330:
	s_waitcnt lgkmcnt(0)
	ds_read_b128 v[130:133], v0 offset:16384
	ds_read_b128 v[134:137], v0 offset:17408
	ds_read_b128 v[138:141], v0 offset:18432
	ds_read_b128 v[142:145], v0 offset:19456
	v_add_u32_e32 v0, s8, v168
	s_add_i32 s8, s34, 3
	s_min_u32 s8, s8, s24
	s_and_b32 s35, s27, 0x18000
	s_lshl_b32 s8, s8, 6
	s_add_i32 s35, s23, s35
	v_add_u32_e32 v0, v0, v169
	v_lshl_add_u64 v[170:171], v[158:159], 0, s[8:9]
	s_mov_b32 m0, s35
	ds_read_b128 v[154:157], v0
	ds_read_b128 v[150:153], v0 offset:1024
	ds_read_b128 v[146:149], v0 offset:2048
	global_load_lds_dwordx4 v[170:171], off
	v_lshl_add_u64 v[170:171], v[160:161], 0, s[8:9]
	s_add_i32 m0, s35, 0x2000
	s_and_b64 vcc, exec, s[0:1]
	global_load_lds_dwordx4 v[170:171], off
	v_lshl_add_u64 v[170:171], v[162:163], 0, s[8:9]
	s_add_i32 m0, s35, 0x4000
	s_nop 0
	global_load_lds_dwordx4 v[170:171], off
	v_lshl_add_u64 v[170:171], v[164:165], 0, s[8:9]
	s_add_i32 m0, s35, 0x6000
	s_nop 0
	global_load_lds_dwordx4 v[170:171], off
	s_cbranch_vccnz .LBB0_1329
	s_waitcnt lgkmcnt(0)
	v_mfma_f32_16x16x32_bf16 v[126:129], v[130:133], v[154:157], v[126:129]
	ds_read_b128 v[170:173], v0 offset:3072
	v_mfma_f32_16x16x32_bf16 v[122:125], v[134:137], v[154:157], v[122:125]
	v_mfma_f32_16x16x32_bf16 v[118:121], v[138:141], v[154:157], v[118:121]
	v_mfma_f32_16x16x32_bf16 v[114:117], v[142:145], v[154:157], v[114:117]
	v_mfma_f32_16x16x32_bf16 v[110:113], v[130:133], v[150:153], v[110:113]
	ds_read_b128 v[154:157], v0 offset:4096
	v_mfma_f32_16x16x32_bf16 v[106:109], v[134:137], v[150:153], v[106:109]
	v_mfma_f32_16x16x32_bf16 v[102:105], v[138:141], v[150:153], v[102:105]
	v_mfma_f32_16x16x32_bf16 v[98:101], v[142:145], v[150:153], v[98:101]
	v_mfma_f32_16x16x32_bf16 v[94:97], v[130:133], v[146:149], v[94:97]
	ds_read_b128 v[150:153], v0 offset:5120
	v_mfma_f32_16x16x32_bf16 v[90:93], v[134:137], v[146:149], v[90:93]
	v_mfma_f32_16x16x32_bf16 v[86:89], v[138:141], v[146:149], v[86:89]
	v_mfma_f32_16x16x32_bf16 v[82:85], v[142:145], v[146:149], v[82:85]
	s_waitcnt lgkmcnt(0)
	v_mfma_f32_16x16x32_bf16 v[78:81], v[130:133], v[170:173], v[78:81]
	ds_read_b128 v[146:149], v0 offset:6144
	v_mfma_f32_16x16x32_bf16 v[74:77], v[134:137], v[170:173], v[74:77]
	v_mfma_f32_16x16x32_bf16 v[70:73], v[138:141], v[170:173], v[70:73]
	v_mfma_f32_16x16x32_bf16 v[66:69], v[142:145], v[170:173], v[66:69]
	v_mfma_f32_16x16x32_bf16 v[62:65], v[130:133], v[154:157], v[62:65]
	ds_read_b128 v[170:173], v0 offset:7168
	v_mfma_f32_16x16x32_bf16 v[58:61], v[134:137], v[154:157], v[58:61]
	v_mfma_f32_16x16x32_bf16 v[54:57], v[138:141], v[154:157], v[54:57]
	v_mfma_f32_16x16x32_bf16 v[50:53], v[142:145], v[154:157], v[50:53]
	v_mfma_f32_16x16x32_bf16 v[46:49], v[130:133], v[150:153], v[46:49]
	v_mfma_f32_16x16x32_bf16 v[42:45], v[134:137], v[150:153], v[42:45]
	v_mfma_f32_16x16x32_bf16 v[38:41], v[138:141], v[150:153], v[38:41]
	v_mfma_f32_16x16x32_bf16 v[34:37], v[142:145], v[150:153], v[34:37]
	s_waitcnt lgkmcnt(0)
	v_mfma_f32_16x16x32_bf16 v[30:33], v[130:133], v[146:149], v[30:33]
	v_mfma_f32_16x16x32_bf16 v[26:29], v[134:137], v[146:149], v[26:29]
	v_mfma_f32_16x16x32_bf16 v[22:25], v[138:141], v[146:149], v[22:25]
	v_mfma_f32_16x16x32_bf16 v[18:21], v[142:145], v[146:149], v[18:21]
	v_mfma_f32_16x16x32_bf16 v[14:17], v[130:133], v[170:173], v[14:17]
	v_mfma_f32_16x16x32_bf16 v[10:13], v[134:137], v[170:173], v[10:13]
	v_mfma_f32_16x16x32_bf16 v[6:9], v[138:141], v[170:173], v[6:9]
	v_mfma_f32_16x16x32_bf16 v[2:5], v[142:145], v[170:173], v[2:5]
	s_branch .LBB0_1329

.LBB0_1580:
	s_ashr_i32 s0, s14, 4
	s_lshl_b32 s1, s14, 8
	s_lshl_b32 s15, s0, 8
	s_and_b32 s16, s1, 0xf00
	v_mov_b32_e32 v10, v174
	s_cmp_lg_u32 s0, 64
	s_cselect_b64 s[0:1], -1, 0
	v_readfirstlane_b32 s6, v10
	s_ashr_i32 s24, s6, 6
	v_bfe_u32 v0, v10, 2, 4
	s_lshl_b32 s20, s24, 4
	v_or_b32_e32 v2, s15, v0
	s_add_i32 s21, s20, 0x80
	v_or_b32_e32 v0, s16, v0
	v_add_u32_e32 v8, s20, v2
	v_add_u32_e32 v2, s21, v2
	v_add_u32_e32 v4, s20, v0
	v_add_u32_e32 v0, s21, v0
	v_mad_i64_i32 v[2:3], s[18:19], v2, s3, v[158:159]
	v_mad_i64_i32 v[4:5], s[18:19], v4, s3, v[160:161]
	v_mad_i64_i32 v[6:7], s[18:19], v0, s3, v[160:161]
	s_and_b32 s17, s24, 3
	s_ashr_i32 s18, s6, 8
	v_mad_i64_i32 v[8:9], s[20:21], v8, s3, v[158:159]
	s_lshl_b32 s19, s18, 13
	s_lshl_b32 s20, s17, 12
	v_bfe_u32 v170, v10, 4, 2
	s_cmp_lg_u32 s18, 1
	v_bitop3_b32 v11, v170, v10, 3 bitop3:0x78
	s_cselect_b64 s[22:23], -1, 0
	s_lshl_b32 s6, s24, 10
	v_lshlrev_b32_e32 v0, 4, v11
	s_add_i32 s21, s6, 0
	v_lshl_add_u64 v[162:163], v[8:9], 0, v[0:1]
	s_mov_b32 m0, s21
	v_lshl_add_u64 v[164:165], v[2:3], 0, v[0:1]
	global_load_lds_dwordx4 v[162:163], off
	s_add_i32 m0, s21, 0x2000
	v_lshl_add_u64 v[166:167], v[4:5], 0, v[0:1]
	global_load_lds_dwordx4 v[164:165], off
	s_add_i32 m0, s21, 0x4000
	v_lshl_add_u64 v[168:169], v[6:7], 0, v[0:1]
	global_load_lds_dwordx4 v[166:167], off
	s_add_i32 m0, s21, 0x6000
	v_lshl_add_u64 v[2:3], v[162:163], 0, 64
	global_load_lds_dwordx4 v[168:169], off
	s_add_i32 m0, s21, 0x8000
	s_add_i32 s24, s6, 0x2000
	global_load_lds_dwordx4 v[2:3], off
	v_lshl_add_u64 v[2:3], v[164:165], 0, 64
	s_add_i32 m0, s21, 0xa000
	v_lshrrev_b32_e32 v0, 2, v10
	global_load_lds_dwordx4 v[2:3], off
	v_lshl_add_u64 v[2:3], v[166:167], 0, 64
	s_add_i32 m0, s21, 0xc000
	v_bitop3_b32 v0, v170, v0, 3 bitop3:0x78
	global_load_lds_dwordx4 v[2:3], off
	v_lshl_add_u64 v[2:3], v[168:169], 0, 64
	s_add_i32 m0, s21, 0xe000
	s_or_b64 s[0:1], s[0:1], s[22:23]
	global_load_lds_dwordx4 v[2:3], off
	v_lshl_add_u64 v[2:3], v[162:163], 0, s[8:9]
	s_add_i32 m0, s10, s6
	v_and_b32_e32 v171, 15, v10
	global_load_lds_dwordx4 v[2:3], off
	v_lshl_add_u64 v[2:3], v[164:165], 0, s[8:9]
	s_add_i32 m0, s10, s24
	v_lshlrev_b32_e32 v172, 4, v0
	global_load_lds_dwordx4 v[2:3], off
	v_lshl_add_u64 v[2:3], v[166:167], 0, s[8:9]
	s_add_i32 m0, s11, s6
	v_mov_b32_e32 v0, v1
	global_load_lds_dwordx4 v[2:3], off
	v_lshl_add_u64 v[2:3], v[168:169], 0, s[8:9]
	s_add_i32 m0, s11, s24
	v_cndmask_b32_e64 v4, 0, 1, s[0:1]
	global_load_lds_dwordx4 v[2:3], off
	s_waitcnt vmcnt(8)
	v_mov_b32_e32 v2, v1
	v_mov_b32_e32 v3, v1
	s_waitcnt lgkmcnt(0)
	s_barrier
	v_mov_b64_e32 v[16:17], v[2:3]
	v_mov_b64_e32 v[24:25], v[2:3]
	v_mov_b64_e32 v[28:29], v[2:3]
	v_mov_b64_e32 v[32:33], v[2:3]
	v_mov_b64_e32 v[36:37], v[2:3]
	v_mov_b64_e32 v[40:41], v[2:3]
	v_mov_b64_e32 v[44:45], v[2:3]
	v_mov_b64_e32 v[48:49], v[2:3]
	v_mov_b64_e32 v[52:53], v[2:3]
	v_mov_b64_e32 v[56:57], v[2:3]
	v_mov_b64_e32 v[60:61], v[2:3]
	v_mov_b64_e32 v[64:65], v[2:3]
	v_mov_b64_e32 v[68:69], v[2:3]
	v_mov_b64_e32 v[72:73], v[2:3]
	v_mov_b64_e32 v[76:77], v[2:3]
	v_mov_b64_e32 v[80:81], v[2:3]
	v_mov_b64_e32 v[84:85], v[2:3]
	v_mov_b64_e32 v[88:89], v[2:3]
	v_mov_b64_e32 v[92:93], v[2:3]
	v_mov_b64_e32 v[96:97], v[2:3]
	v_mov_b64_e32 v[100:101], v[2:3]
	v_mov_b64_e32 v[104:105], v[2:3]
	v_mov_b64_e32 v[108:109], v[2:3]
	v_mov_b64_e32 v[112:113], v[2:3]
	v_mov_b64_e32 v[116:117], v[2:3]
	v_mov_b64_e32 v[120:121], v[2:3]
	v_mov_b64_e32 v[124:125], v[2:3]
	v_mov_b64_e32 v[128:129], v[2:3]
	v_mov_b64_e32 v[20:21], v[2:3]
	v_mov_b64_e32 v[12:13], v[2:3]
	v_mov_b64_e32 v[8:9], v[2:3]
	v_cmp_ne_u32_e64 s[0:1], 1, v4
	v_mov_b64_e32 v[14:15], v[0:1]
	v_mov_b64_e32 v[22:23], v[0:1]
	v_mov_b64_e32 v[26:27], v[0:1]
	v_mov_b64_e32 v[30:31], v[0:1]
	v_mov_b64_e32 v[34:35], v[0:1]
	v_mov_b64_e32 v[38:39], v[0:1]
	v_mov_b64_e32 v[42:43], v[0:1]
	v_mov_b64_e32 v[46:47], v[0:1]
	v_mov_b64_e32 v[50:51], v[0:1]
	v_mov_b64_e32 v[54:55], v[0:1]
	v_mov_b64_e32 v[58:59], v[0:1]
	v_mov_b64_e32 v[62:63], v[0:1]
	v_mov_b64_e32 v[66:67], v[0:1]
	v_mov_b64_e32 v[70:71], v[0:1]
	v_mov_b64_e32 v[74:75], v[0:1]
	v_mov_b64_e32 v[78:79], v[0:1]
	v_mov_b64_e32 v[82:83], v[0:1]
	v_mov_b64_e32 v[86:87], v[0:1]
	v_mov_b64_e32 v[90:91], v[0:1]
	v_mov_b64_e32 v[94:95], v[0:1]
	v_mov_b64_e32 v[98:99], v[0:1]
	v_mov_b64_e32 v[102:103], v[0:1]
	v_mov_b64_e32 v[106:107], v[0:1]
	v_mov_b64_e32 v[110:111], v[0:1]
	v_mov_b64_e32 v[114:115], v[0:1]
	v_mov_b64_e32 v[118:119], v[0:1]
	v_mov_b64_e32 v[122:123], v[0:1]
	v_mov_b64_e32 v[126:127], v[0:1]
	v_mov_b64_e32 v[18:19], v[0:1]
	v_mov_b64_e32 v[10:11], v[0:1]
	v_mov_b64_e32 v[6:7], v[0:1]
	v_mov_b64_e32 v[4:5], v[2:3]
	v_lshlrev_b32_e32 v173, 6, v171
	s_mov_b32 s22, s7
	s_movk_i32 s23, 0x60
	v_mov_b64_e32 v[2:3], v[0:1]
	s_mov_b32 s24, s7
	s_and_b32 s6, s22, 0x18000
	s_add_i32 s6, s6, 0
	s_add_i32 s25, s6, s20
	v_add3_u32 v0, s25, v173, v172
	s_add_i32 s6, s6, s19
	s_branch .LBB0_1582

.Lnd1_wd:
	s_add_i32 s24, s24, 1
	s_add_i32 s23, s23, 32
	s_add_i32 s22, s22, 0x8000
	s_and_b32 s6, s22, 0x18000
	s_add_i32 s6, s6, 0
	s_add_i32 s25, s6, s20
	v_add3_u32 v0, s25, v173, v172
	s_add_i32 s6, s6, s19
	s_cmpk_eq_i32 s23, 0x460
	s_waitcnt lgkmcnt(0)
	s_barrier
	s_cbranch_scc1 .LBB0_1584
.LBB0_1582:
	s_waitcnt lgkmcnt(0)
	ds_read_b128 v[130:133], v0 offset:16384
	ds_read_b128 v[134:137], v0 offset:17408
	ds_read_b128 v[138:141], v0 offset:18432
	ds_read_b128 v[142:145], v0 offset:19456
	v_add_u32_e32 v0, s6, v173
	s_add_i32 s6, s22, 0x18000
	s_and_b32 s25, s6, 0x18000
	s_cmp_lt_u32 s24, 29
	s_cselect_b32 s6, s23, 0x3e0
	s_lshl_b64 s[26:27], s[6:7], 1
	s_add_i32 s6, s21, s25
	v_add_u32_e32 v0, v0, v172
	ds_read_b128 v[154:157], v0
	ds_read_b128 v[150:153], v0 offset:1024
	ds_read_b128 v[146:149], v0 offset:2048
	s_and_b64 vcc, exec, s[0:1]
	s_cmp_lt_u32 s24, 29
	s_cbranch_scc0 .Lnd1_skip
	s_mov_b32 m0, s6
	v_lshl_add_u64 v[194:195], v[162:163], 0, s[26:27]
	global_load_lds_dwordx4 v[194:195], off
	s_add_i32 m0, s6, 0x2000
	v_lshl_add_u64 v[194:195], v[164:165], 0, s[26:27]
	global_load_lds_dwordx4 v[194:195], off
	s_add_i32 m0, s6, 0x4000
	v_lshl_add_u64 v[194:195], v[166:167], 0, s[26:27]
	global_load_lds_dwordx4 v[194:195], off
	s_add_i32 m0, s6, 0x6000
	v_lshl_add_u64 v[194:195], v[168:169], 0, s[26:27]
	global_load_lds_dwordx4 v[194:195], off

.LBB0_1661:
	s_and_b32 vcc_lo, s21, 7
	s_lshl_b32 vcc_lo, vcc_lo, 5
	s_lshr_b32 vcc_hi, s21, 3
	s_or_b32 vcc_lo, vcc_lo, vcc_hi
	s_cmpk_lt_i32 s21, 0x100
	s_cselect_b32 vcc_lo, vcc_lo, s21
	s_cmpk_lt_i32 s21, 0x100
	s_cselect_b64 s[10:11], -1, 0
	s_lshl_b32 s0, vcc_lo, 6
	s_and_b32 s0, s0, 0xffffff00
	s_lshl_b32 s1, vcc_lo, 8
	s_and_b32 s12, s1, 0x300
	s_add_i32 s1, s0, 0xffffc000
	s_cmpk_gt_i32 s21, 0xff
	s_cselect_b32 s22, 0x4000, s0
	s_cselect_b32 s0, s1, 0
	s_cselect_b32 s13, 8, 0x80
	s_ashr_i32 s1, s0, 31
	s_lshl_b64 s[0:1], s[0:1], 1
	s_add_u32 s24, s96, s0
	s_addc_u32 s25, s97, s1
	s_waitcnt vmcnt(1)
	v_mov_b32_e32 v10, v174
	s_add_u32 s0, s92, s0
	s_addc_u32 s1, s93, s1
	v_readfirstlane_b32 s6, v10
	s_ashr_i32 s23, s6, 6
	v_bfe_u32 v0, v10, 2, 4
	s_lshl_b32 s15, s23, 4
	v_or_b32_e32 v2, s22, v0
	s_add_i32 s26, s15, 0x80
	v_or_b32_e32 v0, s12, v0
	s_and_b32 s14, s23, 3
	v_add_u32_e32 v12, s15, v2
	v_add_u32_e32 v4, s26, v2
	v_mov_b64_e32 v[2:3], s[24:25]
	s_waitcnt vmcnt(0)
	v_add_u32_e32 v8, s15, v0
	v_mov_b64_e32 v[6:7], s[0:1]
	v_add_u32_e32 v0, s26, v0
	s_ashr_i32 s15, s6, 8
	v_bfe_u32 v166, v10, 4, 2
	v_mad_i64_i32 v[4:5], s[24:25], v4, s16, v[2:3]
	v_mad_i64_i32 v[8:9], s[0:1], v8, s16, v[6:7]
	v_mad_i64_i32 v[6:7], s[0:1], v0, s16, v[6:7]
	v_mad_i64_i32 v[2:3], s[0:1], v12, s16, v[2:3]
	s_cmp_lg_u32 s15, 1
	v_bitop3_b32 v11, v166, v10, 3 bitop3:0x78
	s_cselect_b64 s[0:1], -1, 0
	s_lshl_b32 s6, s23, 10
	v_lshlrev_b32_e32 v0, 4, v11
	s_add_i32 s23, s6, 0
	v_lshl_add_u64 v[158:159], v[2:3], 0, v[0:1]
	s_mov_b32 m0, s23
	v_lshl_add_u64 v[160:161], v[4:5], 0, v[0:1]
	global_load_lds_dwordx4 v[158:159], off
	s_add_i32 m0, s23, 0x2000
	v_lshl_add_u64 v[162:163], v[8:9], 0, v[0:1]
	global_load_lds_dwordx4 v[160:161], off
	s_add_i32 m0, s23, 0x4000
	v_lshl_add_u64 v[164:165], v[6:7], 0, v[0:1]
	global_load_lds_dwordx4 v[162:163], off
	s_add_i32 m0, s23, 0x6000
	v_lshl_add_u64 v[2:3], v[158:159], 0, 64
	global_load_lds_dwordx4 v[164:165], off
	s_add_i32 m0, s23, 0x8000
	s_add_i32 s24, s6, 0x2000
	global_load_lds_dwordx4 v[2:3], off
	v_lshl_add_u64 v[2:3], v[160:161], 0, 64
	s_add_i32 m0, s23, 0xa000
	v_lshrrev_b32_e32 v0, 2, v10
	global_load_lds_dwordx4 v[2:3], off
	v_lshl_add_u64 v[2:3], v[162:163], 0, 64
	s_add_i32 m0, s23, 0xc000
	v_bitop3_b32 v0, v166, v0, 3 bitop3:0x78
	global_load_lds_dwordx4 v[2:3], off
	v_lshl_add_u64 v[2:3], v[164:165], 0, 64
	s_add_i32 m0, s23, 0xe000
	s_or_b64 s[0:1], s[10:11], s[0:1]
	global_load_lds_dwordx4 v[2:3], off
	v_lshl_add_u64 v[2:3], v[158:159], 0, s[8:9]
	s_add_i32 m0, s18, s6
	v_and_b32_e32 v167, 15, v10
	global_load_lds_dwordx4 v[2:3], off
	v_lshl_add_u64 v[2:3], v[160:161], 0, s[8:9]
	s_add_i32 m0, s18, s24
	v_lshlrev_b32_e32 v169, 4, v0
	global_load_lds_dwordx4 v[2:3], off
	v_lshl_add_u64 v[2:3], v[162:163], 0, s[8:9]
	s_add_i32 m0, s19, s6
	v_mov_b32_e32 v0, v1
	global_load_lds_dwordx4 v[2:3], off
	v_lshl_add_u64 v[2:3], v[164:165], 0, s[8:9]
	s_add_i32 m0, s19, s24
	v_cndmask_b32_e64 v4, 0, 1, s[0:1]
	global_load_lds_dwordx4 v[2:3], off
	s_waitcnt vmcnt(8)
	v_mov_b32_e32 v2, v1
	v_mov_b32_e32 v3, v1
	s_waitcnt lgkmcnt(0)
	s_barrier
	v_mov_b64_e32 v[20:21], v[2:3]
	v_mov_b64_e32 v[24:25], v[2:3]
	v_mov_b64_e32 v[28:29], v[2:3]
	v_mov_b64_e32 v[32:33], v[2:3]
	v_mov_b64_e32 v[36:37], v[2:3]
	v_mov_b64_e32 v[40:41], v[2:3]
	v_mov_b64_e32 v[44:45], v[2:3]
	v_mov_b64_e32 v[48:49], v[2:3]
	v_mov_b64_e32 v[52:53], v[2:3]
	v_mov_b64_e32 v[56:57], v[2:3]
	v_mov_b64_e32 v[60:61], v[2:3]
	v_mov_b64_e32 v[64:65], v[2:3]
	v_mov_b64_e32 v[68:69], v[2:3]
	v_mov_b64_e32 v[72:73], v[2:3]
	v_mov_b64_e32 v[76:77], v[2:3]
	v_mov_b64_e32 v[80:81], v[2:3]
	v_mov_b64_e32 v[84:85], v[2:3]
	v_mov_b64_e32 v[88:89], v[2:3]
	v_mov_b64_e32 v[92:93], v[2:3]
	v_mov_b64_e32 v[96:97], v[2:3]
	v_mov_b64_e32 v[100:101], v[2:3]
	v_mov_b64_e32 v[104:105], v[2:3]
	v_mov_b64_e32 v[108:109], v[2:3]
	v_mov_b64_e32 v[112:113], v[2:3]
	v_mov_b64_e32 v[116:117], v[2:3]
	v_mov_b64_e32 v[120:121], v[2:3]
	v_mov_b64_e32 v[124:125], v[2:3]
	v_mov_b64_e32 v[128:129], v[2:3]
	v_mov_b64_e32 v[16:17], v[2:3]
	v_mov_b64_e32 v[12:13], v[2:3]
	v_mov_b64_e32 v[8:9], v[2:3]
	v_cmp_ne_u32_e64 s[0:1], 1, v4
	v_mov_b64_e32 v[18:19], v[0:1]
	v_mov_b64_e32 v[22:23], v[0:1]
	v_mov_b64_e32 v[26:27], v[0:1]
	v_mov_b64_e32 v[30:31], v[0:1]
	v_mov_b64_e32 v[34:35], v[0:1]
	v_mov_b64_e32 v[38:39], v[0:1]
	v_mov_b64_e32 v[42:43], v[0:1]
	v_mov_b64_e32 v[46:47], v[0:1]
	v_mov_b64_e32 v[50:51], v[0:1]
	v_mov_b64_e32 v[54:55], v[0:1]
	v_mov_b64_e32 v[58:59], v[0:1]
	v_mov_b64_e32 v[62:63], v[0:1]
	v_mov_b64_e32 v[66:67], v[0:1]
	v_mov_b64_e32 v[70:71], v[0:1]
	v_mov_b64_e32 v[74:75], v[0:1]
	v_mov_b64_e32 v[78:79], v[0:1]
	v_mov_b64_e32 v[82:83], v[0:1]
	v_mov_b64_e32 v[86:87], v[0:1]
	v_mov_b64_e32 v[90:91], v[0:1]
	v_mov_b64_e32 v[94:95], v[0:1]
	v_mov_b64_e32 v[98:99], v[0:1]
	v_mov_b64_e32 v[102:103], v[0:1]
	v_mov_b64_e32 v[106:107], v[0:1]
	v_mov_b64_e32 v[110:111], v[0:1]
	v_mov_b64_e32 v[114:115], v[0:1]
	v_mov_b64_e32 v[118:119], v[0:1]
	v_mov_b64_e32 v[122:123], v[0:1]
	v_mov_b64_e32 v[126:127], v[0:1]
	v_mov_b64_e32 v[14:15], v[0:1]
	v_mov_b64_e32 v[10:11], v[0:1]
	v_mov_b64_e32 v[6:7], v[0:1]
	v_mov_b64_e32 v[4:5], v[2:3]
	s_add_i32 s24, s13, -1
	s_lshl_b32 s25, s14, 12
	v_lshlrev_b32_e32 v168, 6, v167
	s_lshl_b32 s26, s15, 13
	s_mov_b32 s27, 0x18000
	v_mov_b64_e32 v[2:3], v[0:1]
	s_mov_b32 s30, s7
	s_add_i32 s6, s27, 0xfffe8000
	s_and_b32 s6, s6, 0x18000
	s_add_i32 s6, s6, 0
	s_add_i32 s31, s6, s25
	v_add3_u32 v0, s31, v168, v169
	s_add_i32 s6, s6, s26
	s_branch .LBB0_1663
.LBB0_1662:
	s_waitcnt vmcnt(8)
	s_add_i32 s30, s30, 1
	s_add_i32 s27, s27, 0x8000
	s_add_i32 s6, s27, 0xfffe8000
	s_and_b32 s6, s6, 0x18000
	s_add_i32 s6, s6, 0
	s_add_i32 s31, s6, s25
	v_add3_u32 v0, s31, v168, v169
	s_add_i32 s6, s6, s26
	s_cmp_eq_u32 s13, s30
	s_waitcnt lgkmcnt(0)
	s_barrier
	s_cbranch_scc1 .LBB0_1665
.LBB0_1663:
	s_waitcnt lgkmcnt(0)
	ds_read_b128 v[130:133], v0 offset:16384
	ds_read_b128 v[134:137], v0 offset:17408
	ds_read_b128 v[138:141], v0 offset:18432
	ds_read_b128 v[142:145], v0 offset:19456
	v_add_u32_e32 v0, s6, v168
	s_add_i32 s6, s30, 3
	s_min_u32 s6, s6, s24
	s_and_b32 s31, s27, 0x18000
	s_lshl_b32 s6, s6, 6
	s_add_i32 s31, s23, s31
	v_add_u32_e32 v0, v0, v169
	v_lshl_add_u64 v[170:171], v[158:159], 0, s[6:7]
	s_mov_b32 m0, s31
	ds_read_b128 v[154:157], v0
	ds_read_b128 v[150:153], v0 offset:1024
	ds_read_b128 v[146:149], v0 offset:2048
	global_load_lds_dwordx4 v[170:171], off
	v_lshl_add_u64 v[170:171], v[160:161], 0, s[6:7]
	s_add_i32 m0, s31, 0x2000
	s_and_b64 vcc, exec, s[0:1]
	global_load_lds_dwordx4 v[170:171], off
	v_lshl_add_u64 v[170:171], v[162:163], 0, s[6:7]
	s_add_i32 m0, s31, 0x4000
	s_nop 0
	global_load_lds_dwordx4 v[170:171], off
	v_lshl_add_u64 v[170:171], v[164:165], 0, s[6:7]
	s_add_i32 m0, s31, 0x6000
	s_nop 0
	global_load_lds_dwordx4 v[170:171], off
	s_cbranch_vccnz .LBB0_1662
	s_waitcnt lgkmcnt(0)
	v_mfma_f32_16x16x32_bf16 v[126:129], v[130:133], v[154:157], v[126:129]
	ds_read_b128 v[170:173], v0 offset:3072
	v_mfma_f32_16x16x32_bf16 v[122:125], v[134:137], v[154:157], v[122:125]
	v_mfma_f32_16x16x32_bf16 v[118:121], v[138:141], v[154:157], v[118:121]
	v_mfma_f32_16x16x32_bf16 v[114:117], v[142:145], v[154:157], v[114:117]
	v_mfma_f32_16x16x32_bf16 v[110:113], v[130:133], v[150:153], v[110:113]
	ds_read_b128 v[154:157], v0 offset:4096
	v_mfma_f32_16x16x32_bf16 v[106:109], v[134:137], v[150:153], v[106:109]
	v_mfma_f32_16x16x32_bf16 v[102:105], v[138:141], v[150:153], v[102:105]
	v_mfma_f32_16x16x32_bf16 v[98:101], v[142:145], v[150:153], v[98:101]
	v_mfma_f32_16x16x32_bf16 v[94:97], v[130:133], v[146:149], v[94:97]
	ds_read_b128 v[150:153], v0 offset:5120
	v_mfma_f32_16x16x32_bf16 v[90:93], v[134:137], v[146:149], v[90:93]
	v_mfma_f32_16x16x32_bf16 v[86:89], v[138:141], v[146:149], v[86:89]
	v_mfma_f32_16x16x32_bf16 v[82:85], v[142:145], v[146:149], v[82:85]
	s_waitcnt lgkmcnt(0)
	v_mfma_f32_16x16x32_bf16 v[78:81], v[130:133], v[170:173], v[78:81]
	ds_read_b128 v[146:149], v0 offset:6144
	v_mfma_f32_16x16x32_bf16 v[74:77], v[134:137], v[170:173], v[74:77]
	v_mfma_f32_16x16x32_bf16 v[70:73], v[138:141], v[170:173], v[70:73]
	v_mfma_f32_16x16x32_bf16 v[66:69], v[142:145], v[170:173], v[66:69]
	v_mfma_f32_16x16x32_bf16 v[62:65], v[130:133], v[154:157], v[62:65]
	ds_read_b128 v[170:173], v0 offset:7168
	v_mfma_f32_16x16x32_bf16 v[58:61], v[134:137], v[154:157], v[58:61]
	v_mfma_f32_16x16x32_bf16 v[54:57], v[138:141], v[154:157], v[54:57]
	v_mfma_f32_16x16x32_bf16 v[50:53], v[142:145], v[154:157], v[50:53]
	v_mfma_f32_16x16x32_bf16 v[46:49], v[130:133], v[150:153], v[46:49]
	v_mfma_f32_16x16x32_bf16 v[42:45], v[134:137], v[150:153], v[42:45]
	v_mfma_f32_16x16x32_bf16 v[38:41], v[138:141], v[150:153], v[38:41]
	v_mfma_f32_16x16x32_bf16 v[34:37], v[142:145], v[150:153], v[34:37]
	s_waitcnt lgkmcnt(0)
	v_mfma_f32_16x16x32_bf16 v[30:33], v[130:133], v[146:149], v[30:33]
	v_mfma_f32_16x16x32_bf16 v[26:29], v[134:137], v[146:149], v[26:29]
	v_mfma_f32_16x16x32_bf16 v[22:25], v[138:141], v[146:149], v[22:25]
	v_mfma_f32_16x16x32_bf16 v[18:21], v[142:145], v[146:149], v[18:21]
	v_mfma_f32_16x16x32_bf16 v[14:17], v[130:133], v[170:173], v[14:17]
	v_mfma_f32_16x16x32_bf16 v[10:13], v[134:137], v[170:173], v[10:13]
	v_mfma_f32_16x16x32_bf16 v[6:9], v[138:141], v[170:173], v[6:9]
	v_mfma_f32_16x16x32_bf16 v[2:5], v[142:145], v[170:173], v[2:5]
	s_branch .LBB0_1662

.LBB0_1913:
	s_mul_hi_i32 s0, s61, 0x2aaaaaab
	s_lshr_b32 s1, s0, 31
	s_add_i32 s0, s0, s1
	s_mul_i32 s1, s0, 6
	s_sub_i32 s1, s61, s1
	s_lshl_b32 s62, s0, 8
	s_lshl_b32 s4, s1, 8
	s_waitcnt vmcnt(1)
	v_mov_b32_e32 v10, v174
	s_cmpk_lt_i32 s61, 0x180
	s_cselect_b64 s[0:1], -1, 0
	v_readfirstlane_b32 s5, v10
	s_ashr_i32 s12, s5, 6
	v_bfe_u32 v0, v10, 2, 4
	s_lshl_b32 s7, s12, 4
	v_or_b32_e32 v2, s62, v0
	s_add_i32 s10, s7, 0x80
	v_or_b32_e32 v0, s4, v0
	s_waitcnt vmcnt(0)
	v_add_u32_e32 v8, s7, v2
	v_add_u32_e32 v2, s10, v2
	v_add_u32_e32 v4, s7, v0
	v_add_u32_e32 v0, s10, v0
	s_and_b32 s6, s12, 3
	v_mad_i64_i32 v[2:3], s[8:9], v2, s3, v[158:159]
	v_mad_i64_i32 v[4:5], s[8:9], v4, s3, v[160:161]
	v_mad_i64_i32 v[6:7], s[8:9], v0, s3, v[160:161]
	s_ashr_i32 s5, s5, 8
	v_mad_i64_i32 v[8:9], s[8:9], v8, s3, v[158:159]
	s_lshl_b32 s7, s5, 13
	s_lshl_b32 s8, s6, 12
	v_bfe_u32 v172, v10, 4, 2
	s_cmp_lg_u32 s5, 1
	v_bitop3_b32 v11, v172, v10, 3 bitop3:0x78
	s_cselect_b64 s[10:11], -1, 0
	s_lshl_b32 s12, s12, 10
	v_lshlrev_b32_e32 v0, 4, v11
	s_add_i32 s9, s12, 0
	v_lshl_add_u64 v[162:163], v[8:9], 0, v[0:1]
	s_mov_b32 m0, s9
	v_lshl_add_u64 v[164:165], v[2:3], 0, v[0:1]
	global_load_lds_dwordx4 v[162:163], off
	s_add_i32 m0, s9, 0x2000
	v_lshl_add_u64 v[166:167], v[4:5], 0, v[0:1]
	global_load_lds_dwordx4 v[164:165], off
	s_add_i32 m0, s9, 0x4000
	v_lshl_add_u64 v[168:169], v[6:7], 0, v[0:1]
	global_load_lds_dwordx4 v[166:167], off
	s_add_i32 m0, s9, 0x6000
	v_lshl_add_u64 v[2:3], v[162:163], 0, 64
	global_load_lds_dwordx4 v[168:169], off
	s_add_i32 m0, s9, 0x8000
	s_add_i32 s13, s12, 0x2000
	global_load_lds_dwordx4 v[2:3], off
	v_lshl_add_u64 v[2:3], v[164:165], 0, 64
	s_add_i32 m0, s9, 0xa000
	v_lshrrev_b32_e32 v0, 2, v10
	global_load_lds_dwordx4 v[2:3], off
	v_lshl_add_u64 v[2:3], v[166:167], 0, 64
	s_add_i32 m0, s9, 0xc000
	v_bitop3_b32 v0, v172, v0, 3 bitop3:0x78
	global_load_lds_dwordx4 v[2:3], off
	v_lshl_add_u64 v[2:3], v[168:169], 0, 64
	s_add_i32 m0, s9, 0xe000
	v_and_b32_e32 v173, 63, v10
	global_load_lds_dwordx4 v[2:3], off
	v_lshl_add_u64 v[2:3], v[162:163], 0, s[28:29]
	s_add_i32 m0, s44, s12
	v_and_b32_e32 v176, 15, v10
	global_load_lds_dwordx4 v[2:3], off
	v_lshl_add_u64 v[2:3], v[164:165], 0, s[28:29]
	s_add_i32 m0, s44, s13
	v_lshlrev_b32_e32 v177, 4, v0
	global_load_lds_dwordx4 v[2:3], off
	v_lshl_add_u64 v[2:3], v[166:167], 0, s[28:29]
	s_add_i32 m0, s45, s12
	v_mov_b32_e32 v0, v1
	global_load_lds_dwordx4 v[2:3], off
	v_lshl_add_u64 v[2:3], v[168:169], 0, s[28:29]
	s_add_i32 m0, s45, s13
	v_lshlrev_b32_e32 v178, 6, v176
	global_load_lds_dwordx4 v[2:3], off
	s_waitcnt vmcnt(8)
	v_mov_b32_e32 v2, v1
	v_mov_b32_e32 v3, v1
	s_waitcnt lgkmcnt(0)
	s_barrier
	v_mov_b64_e32 v[20:21], v[2:3]
	v_mov_b64_e32 v[24:25], v[2:3]
	v_mov_b64_e32 v[28:29], v[2:3]
	v_mov_b64_e32 v[32:33], v[2:3]
	v_mov_b64_e32 v[36:37], v[2:3]
	v_mov_b64_e32 v[40:41], v[2:3]
	v_mov_b64_e32 v[44:45], v[2:3]
	v_mov_b64_e32 v[48:49], v[2:3]
	v_mov_b64_e32 v[52:53], v[2:3]
	v_mov_b64_e32 v[56:57], v[2:3]
	v_mov_b64_e32 v[60:61], v[2:3]
	v_mov_b64_e32 v[64:65], v[2:3]
	v_mov_b64_e32 v[68:69], v[2:3]
	v_mov_b64_e32 v[72:73], v[2:3]
	v_mov_b64_e32 v[76:77], v[2:3]
	v_mov_b64_e32 v[80:81], v[2:3]
	v_mov_b64_e32 v[84:85], v[2:3]
	v_mov_b64_e32 v[88:89], v[2:3]
	v_mov_b64_e32 v[92:93], v[2:3]
	v_mov_b64_e32 v[96:97], v[2:3]
	v_mov_b64_e32 v[100:101], v[2:3]
	v_mov_b64_e32 v[104:105], v[2:3]
	v_mov_b64_e32 v[108:109], v[2:3]
	v_mov_b64_e32 v[112:113], v[2:3]
	v_mov_b64_e32 v[116:117], v[2:3]
	v_mov_b64_e32 v[120:121], v[2:3]
	v_mov_b64_e32 v[124:125], v[2:3]
	v_mov_b64_e32 v[128:129], v[2:3]
	v_mov_b64_e32 v[16:17], v[2:3]
	v_mov_b64_e32 v[12:13], v[2:3]
	v_mov_b64_e32 v[8:9], v[2:3]
	v_mov_b64_e32 v[18:19], v[0:1]
	v_mov_b64_e32 v[22:23], v[0:1]
	v_mov_b64_e32 v[26:27], v[0:1]
	v_mov_b64_e32 v[30:31], v[0:1]
	v_mov_b64_e32 v[34:35], v[0:1]
	v_mov_b64_e32 v[38:39], v[0:1]
	v_mov_b64_e32 v[42:43], v[0:1]
	v_mov_b64_e32 v[46:47], v[0:1]
	v_mov_b64_e32 v[50:51], v[0:1]
	v_mov_b64_e32 v[54:55], v[0:1]
	v_mov_b64_e32 v[58:59], v[0:1]
	v_mov_b64_e32 v[62:63], v[0:1]
	v_mov_b64_e32 v[66:67], v[0:1]
	v_mov_b64_e32 v[70:71], v[0:1]
	v_mov_b64_e32 v[74:75], v[0:1]
	v_mov_b64_e32 v[78:79], v[0:1]
	v_mov_b64_e32 v[82:83], v[0:1]
	v_mov_b64_e32 v[86:87], v[0:1]
	v_mov_b64_e32 v[90:91], v[0:1]
	v_mov_b64_e32 v[94:95], v[0:1]
	v_mov_b64_e32 v[98:99], v[0:1]
	v_mov_b64_e32 v[102:103], v[0:1]
	v_mov_b64_e32 v[106:107], v[0:1]
	v_mov_b64_e32 v[110:111], v[0:1]
	v_mov_b64_e32 v[114:115], v[0:1]
	v_mov_b64_e32 v[118:119], v[0:1]
	v_mov_b64_e32 v[122:123], v[0:1]
	v_mov_b64_e32 v[126:127], v[0:1]
	v_mov_b64_e32 v[14:15], v[0:1]
	v_mov_b64_e32 v[10:11], v[0:1]
	v_mov_b64_e32 v[6:7], v[0:1]
	v_mov_b64_e32 v[4:5], v[2:3]
	s_or_b64 s[0:1], s[0:1], s[10:11]
	s_mov_b32 s10, s19
	s_movk_i32 s11, 0x60
	v_mov_b64_e32 v[2:3], v[0:1]
	s_mov_b32 s12, s19
	s_and_b32 s13, s10, 0x18000
	s_add_i32 s13, s13, 0
	s_add_i32 s14, s13, s8
	v_add3_u32 v0, s14, v178, v177
	s_add_i32 s13, s13, s7
	s_branch .LBB0_1915

.Lnd2_wd:
	s_add_i32 s12, s12, 1
	s_add_i32 s11, s11, 32
	s_add_i32 s10, s10, 0x8000
	s_and_b32 s13, s10, 0x18000
	s_add_i32 s13, s13, 0
	s_add_i32 s14, s13, s8
	v_add3_u32 v0, s14, v178, v177
	s_add_i32 s13, s13, s7
	s_cmpk_eq_i32 s11, 0x460
	s_waitcnt lgkmcnt(0)
	s_barrier
	s_cbranch_scc1 .LBB0_1917
.LBB0_1915:
	s_waitcnt lgkmcnt(0)
	ds_read_b128 v[130:133], v0 offset:16384
	ds_read_b128 v[134:137], v0 offset:17408
	ds_read_b128 v[138:141], v0 offset:18432
	ds_read_b128 v[142:145], v0 offset:19456
	v_add_u32_e32 v0, s13, v178
	s_add_i32 s13, s10, 0x18000
	s_and_b32 s13, s13, 0x18000
	s_cmp_lt_u32 s12, 29
	s_cselect_b32 s18, s11, 0x3e0
	s_lshl_b64 s[14:15], s[18:19], 1
	s_add_i32 s13, s9, s13
	v_add_u32_e32 v0, v0, v177
	ds_read_b128 v[154:157], v0
	ds_read_b128 v[150:153], v0 offset:1024
	ds_read_b128 v[146:149], v0 offset:2048
	s_andn2_b64 vcc, exec, s[0:1]
	s_cmp_lt_u32 s12, 29
	s_cbranch_scc0 .Lnd2_skip
	s_mov_b32 m0, s13
	v_lshl_add_u64 v[194:195], v[162:163], 0, s[14:15]
	global_load_lds_dwordx4 v[194:195], off
	s_add_i32 m0, s13, 0x2000
	v_lshl_add_u64 v[194:195], v[164:165], 0, s[14:15]
	global_load_lds_dwordx4 v[194:195], off
	s_add_i32 m0, s13, 0x4000
	v_lshl_add_u64 v[194:195], v[166:167], 0, s[14:15]
	global_load_lds_dwordx4 v[194:195], off
	s_add_i32 m0, s13, 0x6000
	v_lshl_add_u64 v[194:195], v[168:169], 0, s[14:15]
	global_load_lds_dwordx4 v[194:195], off

.LBB0_2753:
	s_and_b32 vcc_lo, s19, 7
	s_lshl_b32 vcc_lo, vcc_lo, 5
	s_lshr_b32 vcc_hi, s19, 3
	s_or_b32 vcc_lo, vcc_lo, vcc_hi
	s_cmpk_lt_i32 s19, 0x100
	s_cselect_b32 vcc_lo, vcc_lo, s19
	s_cmpk_lt_i32 s19, 0x100
	s_cselect_b64 s[8:9], -1, 0
	s_lshl_b32 s1, vcc_lo, 8
	s_and_b32 s10, s1, 0x300
	s_lshl_b32 s1, s19, 4
	s_lshl_b32 s0, vcc_lo, 6
	s_andn2_b32 s1, s1, 63
	s_and_b32 s0, s0, 0xffffff00
	s_addk_i32 s1, 0xf000
	s_cmpk_gt_i32 s19, 0xff
	s_cselect_b32 s20, 0x4000, s0
	s_cselect_b32 s0, s1, 0
	s_cselect_b32 s11, 2, 32
	s_cselect_b32 s6, 64, 0x80
	s_ashr_i32 s1, s0, 31
	s_lshl_b64 s[0:1], s[0:1], 1
	s_add_u32 s22, s60, s0
	s_waitcnt vmcnt(1)
	v_mov_b32_e32 v10, v174
	s_addc_u32 s23, s61, s1
	v_readlane_b32 s24, v192, 31
	v_readlane_b32 s25, v192, 32
	v_readfirstlane_b32 s13, v10
	s_add_u32 s0, s24, s0
	s_addc_u32 s1, s25, s1
	s_ashr_i32 s21, s13, 6
	v_bfe_u32 v0, v10, 2, 4
	s_lshl_b32 s24, s21, 4
	v_or_b32_e32 v2, s20, v0
	s_add_i32 s25, s24, 0x80
	v_or_b32_e32 v0, s10, v0
	s_and_b32 s12, s21, 3
	v_add_u32_e32 v12, s24, v2
	v_add_u32_e32 v4, s25, v2
	v_mov_b64_e32 v[2:3], s[22:23]
	s_waitcnt vmcnt(0)
	v_add_u32_e32 v8, s24, v0
	v_mov_b64_e32 v[6:7], s[0:1]
	v_add_u32_e32 v0, s25, v0
	s_ashr_i32 s13, s13, 8
	v_bfe_u32 v166, v10, 4, 2
	v_mad_i64_i32 v[4:5], s[22:23], v4, s14, v[2:3]
	v_mad_i64_i32 v[8:9], s[0:1], v8, s14, v[6:7]
	v_mad_i64_i32 v[6:7], s[0:1], v0, s14, v[6:7]
	v_mad_i64_i32 v[2:3], s[0:1], v12, s14, v[2:3]
	s_cmp_lg_u32 s13, 1
	v_bitop3_b32 v11, v166, v10, 3 bitop3:0x78
	s_cselect_b64 s[0:1], -1, 0
	s_lshl_b32 s22, s21, 10
	v_lshlrev_b32_e32 v0, 4, v11
	s_add_i32 s21, s22, 0
	v_lshl_add_u64 v[158:159], v[2:3], 0, v[0:1]
	s_mov_b32 m0, s21
	v_lshl_add_u64 v[160:161], v[4:5], 0, v[0:1]
	global_load_lds_dwordx4 v[158:159], off
	s_add_i32 m0, s21, 0x2000
	v_lshl_add_u64 v[162:163], v[8:9], 0, v[0:1]
	global_load_lds_dwordx4 v[160:161], off
	s_add_i32 m0, s21, 0x4000
	v_lshl_add_u64 v[164:165], v[6:7], 0, v[0:1]
	global_load_lds_dwordx4 v[162:163], off
	s_add_i32 m0, s21, 0x6000
	v_lshl_add_u64 v[2:3], v[158:159], 0, 64
	global_load_lds_dwordx4 v[164:165], off
	s_add_i32 m0, s21, 0x8000
	s_add_i32 s23, s22, 0x2000
	global_load_lds_dwordx4 v[2:3], off
	v_lshl_add_u64 v[2:3], v[160:161], 0, 64
	s_add_i32 m0, s21, 0xa000
	v_lshrrev_b32_e32 v0, 2, v10
	global_load_lds_dwordx4 v[2:3], off
	v_lshl_add_u64 v[2:3], v[162:163], 0, 64
	s_add_i32 m0, s21, 0xc000
	v_bitop3_b32 v0, v166, v0, 3 bitop3:0x78
	global_load_lds_dwordx4 v[2:3], off
	v_lshl_add_u64 v[2:3], v[164:165], 0, 64
	s_add_i32 m0, s21, 0xe000
	s_or_b64 s[0:1], s[8:9], s[0:1]
	global_load_lds_dwordx4 v[2:3], off
	v_lshl_add_u64 v[2:3], v[158:159], 0, s[6:7]
	s_add_i32 m0, s16, s22
	v_and_b32_e32 v167, 15, v10
	global_load_lds_dwordx4 v[2:3], off
	v_lshl_add_u64 v[2:3], v[160:161], 0, s[6:7]
	s_add_i32 m0, s16, s23
	v_lshlrev_b32_e32 v169, 4, v0
	global_load_lds_dwordx4 v[2:3], off
	v_lshl_add_u64 v[2:3], v[162:163], 0, s[6:7]
	s_add_i32 m0, s17, s22
	v_mov_b32_e32 v0, v1
	global_load_lds_dwordx4 v[2:3], off
	v_lshl_add_u64 v[2:3], v[164:165], 0, s[6:7]
	s_add_i32 m0, s17, s23
	v_cndmask_b32_e64 v4, 0, 1, s[0:1]
	global_load_lds_dwordx4 v[2:3], off
	s_waitcnt vmcnt(8)
	v_mov_b32_e32 v2, v1
	v_mov_b32_e32 v3, v1
	s_waitcnt lgkmcnt(0)
	s_barrier
	v_mov_b64_e32 v[20:21], v[2:3]
	v_mov_b64_e32 v[24:25], v[2:3]
	v_mov_b64_e32 v[28:29], v[2:3]
	v_mov_b64_e32 v[32:33], v[2:3]
	v_mov_b64_e32 v[36:37], v[2:3]
	v_mov_b64_e32 v[40:41], v[2:3]
	v_mov_b64_e32 v[44:45], v[2:3]
	v_mov_b64_e32 v[48:49], v[2:3]
	v_mov_b64_e32 v[52:53], v[2:3]
	v_mov_b64_e32 v[56:57], v[2:3]
	v_mov_b64_e32 v[60:61], v[2:3]
	v_mov_b64_e32 v[64:65], v[2:3]
	v_mov_b64_e32 v[68:69], v[2:3]
	v_mov_b64_e32 v[72:73], v[2:3]
	v_mov_b64_e32 v[76:77], v[2:3]
	v_mov_b64_e32 v[80:81], v[2:3]
	v_mov_b64_e32 v[84:85], v[2:3]
	v_mov_b64_e32 v[88:89], v[2:3]
	v_mov_b64_e32 v[92:93], v[2:3]
	v_mov_b64_e32 v[96:97], v[2:3]
	v_mov_b64_e32 v[100:101], v[2:3]
	v_mov_b64_e32 v[104:105], v[2:3]
	v_mov_b64_e32 v[108:109], v[2:3]
	v_mov_b64_e32 v[112:113], v[2:3]
	v_mov_b64_e32 v[116:117], v[2:3]
	v_mov_b64_e32 v[120:121], v[2:3]
	v_mov_b64_e32 v[124:125], v[2:3]
	v_mov_b64_e32 v[128:129], v[2:3]
	v_mov_b64_e32 v[16:17], v[2:3]
	v_mov_b64_e32 v[12:13], v[2:3]
	v_mov_b64_e32 v[8:9], v[2:3]
	v_cmp_ne_u32_e64 s[0:1], 1, v4
	v_mov_b64_e32 v[18:19], v[0:1]
	v_mov_b64_e32 v[22:23], v[0:1]
	v_mov_b64_e32 v[26:27], v[0:1]
	v_mov_b64_e32 v[30:31], v[0:1]
	v_mov_b64_e32 v[34:35], v[0:1]
	v_mov_b64_e32 v[38:39], v[0:1]
	v_mov_b64_e32 v[42:43], v[0:1]
	v_mov_b64_e32 v[46:47], v[0:1]
	v_mov_b64_e32 v[50:51], v[0:1]
	v_mov_b64_e32 v[54:55], v[0:1]
	v_mov_b64_e32 v[58:59], v[0:1]
	v_mov_b64_e32 v[62:63], v[0:1]
	v_mov_b64_e32 v[66:67], v[0:1]
	v_mov_b64_e32 v[70:71], v[0:1]
	v_mov_b64_e32 v[74:75], v[0:1]
	v_mov_b64_e32 v[78:79], v[0:1]
	v_mov_b64_e32 v[82:83], v[0:1]
	v_mov_b64_e32 v[86:87], v[0:1]
	v_mov_b64_e32 v[90:91], v[0:1]
	v_mov_b64_e32 v[94:95], v[0:1]
	v_mov_b64_e32 v[98:99], v[0:1]
	v_mov_b64_e32 v[102:103], v[0:1]
	v_mov_b64_e32 v[106:107], v[0:1]
	v_mov_b64_e32 v[110:111], v[0:1]
	v_mov_b64_e32 v[114:115], v[0:1]
	v_mov_b64_e32 v[118:119], v[0:1]
	v_mov_b64_e32 v[122:123], v[0:1]
	v_mov_b64_e32 v[126:127], v[0:1]
	v_mov_b64_e32 v[14:15], v[0:1]
	v_mov_b64_e32 v[10:11], v[0:1]
	v_mov_b64_e32 v[6:7], v[0:1]
	v_mov_b64_e32 v[4:5], v[2:3]
	s_add_i32 s22, s11, -1
	s_lshl_b32 s23, s12, 12
	v_lshlrev_b32_e32 v168, 6, v167
	s_lshl_b32 s24, s13, 13
	s_mov_b32 s25, 0x18000
	v_mov_b64_e32 v[2:3], v[0:1]
	s_mov_b32 s26, s7
	s_add_i32 s6, s25, 0xfffe8000
	s_and_b32 s6, s6, 0x18000
	s_add_i32 s6, s6, 0
	s_add_i32 s27, s6, s23
	v_add3_u32 v0, s27, v168, v169
	s_add_i32 s6, s6, s24
	s_branch .LBB0_2755
.LBB0_2754:
	s_waitcnt vmcnt(8)
	s_add_i32 s26, s26, 1
	s_add_i32 s25, s25, 0x8000
	s_add_i32 s6, s25, 0xfffe8000
	s_and_b32 s6, s6, 0x18000
	s_add_i32 s6, s6, 0
	s_add_i32 s27, s6, s23
	v_add3_u32 v0, s27, v168, v169
	s_add_i32 s6, s6, s24
	s_cmp_eq_u32 s11, s26
	s_waitcnt lgkmcnt(0)
	s_barrier
	s_cbranch_scc1 .LBB0_2757
.LBB0_2755:
	s_waitcnt lgkmcnt(0)
	ds_read_b128 v[130:133], v0 offset:16384
	ds_read_b128 v[134:137], v0 offset:17408
	ds_read_b128 v[138:141], v0 offset:18432
	ds_read_b128 v[142:145], v0 offset:19456
	v_add_u32_e32 v0, s6, v168
	s_add_i32 s6, s26, 3
	s_min_u32 s6, s6, s22
	s_and_b32 s27, s25, 0x18000
	s_lshl_b32 s6, s6, 6
	s_add_i32 s27, s21, s27
	v_add_u32_e32 v0, v0, v169
	v_lshl_add_u64 v[170:171], v[158:159], 0, s[6:7]
	s_mov_b32 m0, s27
	ds_read_b128 v[154:157], v0
	ds_read_b128 v[150:153], v0 offset:1024
	ds_read_b128 v[146:149], v0 offset:2048
	global_load_lds_dwordx4 v[170:171], off
	v_lshl_add_u64 v[170:171], v[160:161], 0, s[6:7]
	s_add_i32 m0, s27, 0x2000
	s_and_b64 vcc, exec, s[0:1]
	global_load_lds_dwordx4 v[170:171], off
	v_lshl_add_u64 v[170:171], v[162:163], 0, s[6:7]
	s_add_i32 m0, s27, 0x4000
	s_nop 0
	global_load_lds_dwordx4 v[170:171], off
	v_lshl_add_u64 v[170:171], v[164:165], 0, s[6:7]
	s_add_i32 m0, s27, 0x6000
	s_nop 0
	global_load_lds_dwordx4 v[170:171], off
	s_cbranch_vccnz .LBB0_2754
	s_waitcnt lgkmcnt(0)
	v_mfma_f32_16x16x32_bf16 v[126:129], v[130:133], v[154:157], v[126:129]
	ds_read_b128 v[170:173], v0 offset:3072
	v_mfma_f32_16x16x32_bf16 v[122:125], v[134:137], v[154:157], v[122:125]
	v_mfma_f32_16x16x32_bf16 v[118:121], v[138:141], v[154:157], v[118:121]
	v_mfma_f32_16x16x32_bf16 v[114:117], v[142:145], v[154:157], v[114:117]
	v_mfma_f32_16x16x32_bf16 v[110:113], v[130:133], v[150:153], v[110:113]
	ds_read_b128 v[154:157], v0 offset:4096
	v_mfma_f32_16x16x32_bf16 v[106:109], v[134:137], v[150:153], v[106:109]
	v_mfma_f32_16x16x32_bf16 v[102:105], v[138:141], v[150:153], v[102:105]
	v_mfma_f32_16x16x32_bf16 v[98:101], v[142:145], v[150:153], v[98:101]
	v_mfma_f32_16x16x32_bf16 v[94:97], v[130:133], v[146:149], v[94:97]
	ds_read_b128 v[150:153], v0 offset:5120
	v_mfma_f32_16x16x32_bf16 v[90:93], v[134:137], v[146:149], v[90:93]
	v_mfma_f32_16x16x32_bf16 v[86:89], v[138:141], v[146:149], v[86:89]
	v_mfma_f32_16x16x32_bf16 v[82:85], v[142:145], v[146:149], v[82:85]
	s_waitcnt lgkmcnt(0)
	v_mfma_f32_16x16x32_bf16 v[78:81], v[130:133], v[170:173], v[78:81]
	ds_read_b128 v[146:149], v0 offset:6144
	v_mfma_f32_16x16x32_bf16 v[74:77], v[134:137], v[170:173], v[74:77]
	v_mfma_f32_16x16x32_bf16 v[70:73], v[138:141], v[170:173], v[70:73]
	v_mfma_f32_16x16x32_bf16 v[66:69], v[142:145], v[170:173], v[66:69]
	v_mfma_f32_16x16x32_bf16 v[62:65], v[130:133], v[154:157], v[62:65]
	ds_read_b128 v[170:173], v0 offset:7168
	v_mfma_f32_16x16x32_bf16 v[58:61], v[134:137], v[154:157], v[58:61]
	v_mfma_f32_16x16x32_bf16 v[54:57], v[138:141], v[154:157], v[54:57]
	v_mfma_f32_16x16x32_bf16 v[50:53], v[142:145], v[154:157], v[50:53]
	v_mfma_f32_16x16x32_bf16 v[46:49], v[130:133], v[150:153], v[46:49]
	v_mfma_f32_16x16x32_bf16 v[42:45], v[134:137], v[150:153], v[42:45]
	v_mfma_f32_16x16x32_bf16 v[38:41], v[138:141], v[150:153], v[38:41]
	v_mfma_f32_16x16x32_bf16 v[34:37], v[142:145], v[150:153], v[34:37]
	s_waitcnt lgkmcnt(0)
	v_mfma_f32_16x16x32_bf16 v[30:33], v[130:133], v[146:149], v[30:33]
	v_mfma_f32_16x16x32_bf16 v[26:29], v[134:137], v[146:149], v[26:29]
	v_mfma_f32_16x16x32_bf16 v[22:25], v[138:141], v[146:149], v[22:25]
	v_mfma_f32_16x16x32_bf16 v[18:21], v[142:145], v[146:149], v[18:21]
	v_mfma_f32_16x16x32_bf16 v[14:17], v[130:133], v[170:173], v[14:17]
	v_mfma_f32_16x16x32_bf16 v[10:13], v[134:137], v[170:173], v[10:13]
	v_mfma_f32_16x16x32_bf16 v[6:9], v[138:141], v[170:173], v[6:9]
	v_mfma_f32_16x16x32_bf16 v[2:5], v[142:145], v[170:173], v[2:5]
	s_branch .LBB0_2754

.LBB0_3005:
	s_ashr_i32 s0, s12, 4
	s_lshl_b32 s1, s12, 8
	s_lshl_b32 s13, s0, 8
	s_and_b32 s14, s1, 0xf00
	v_mov_b32_e32 v10, v174
	s_cmp_lg_u32 s0, 64
	s_cselect_b64 s[0:1], -1, 0
	v_readfirstlane_b32 s4, v10
	s_ashr_i32 s22, s4, 6
	v_bfe_u32 v0, v10, 2, 4
	s_lshl_b32 s18, s22, 4
	v_or_b32_e32 v2, s13, v0
	s_add_i32 s19, s18, 0x80
	v_or_b32_e32 v0, s14, v0
	v_add_u32_e32 v8, s18, v2
	v_add_u32_e32 v2, s19, v2
	v_add_u32_e32 v4, s18, v0
	v_add_u32_e32 v0, s19, v0
	v_mad_i64_i32 v[2:3], s[16:17], v2, s3, v[158:159]
	v_mad_i64_i32 v[4:5], s[16:17], v4, s3, v[160:161]
	v_mad_i64_i32 v[6:7], s[16:17], v0, s3, v[160:161]
	s_and_b32 s15, s22, 3
	s_ashr_i32 s16, s4, 8
	v_mad_i64_i32 v[8:9], s[18:19], v8, s3, v[158:159]
	s_lshl_b32 s17, s16, 13
	s_lshl_b32 s18, s15, 12
	v_bfe_u32 v170, v10, 4, 2
	s_cmp_lg_u32 s16, 1
	v_bitop3_b32 v11, v170, v10, 3 bitop3:0x78
	s_cselect_b64 s[20:21], -1, 0
	s_lshl_b32 s4, s22, 10
	v_lshlrev_b32_e32 v0, 4, v11
	s_add_i32 s19, s4, 0
	v_lshl_add_u64 v[162:163], v[8:9], 0, v[0:1]
	s_mov_b32 m0, s19
	v_lshl_add_u64 v[164:165], v[2:3], 0, v[0:1]
	global_load_lds_dwordx4 v[162:163], off
	s_add_i32 m0, s19, 0x2000
	v_lshl_add_u64 v[166:167], v[4:5], 0, v[0:1]
	global_load_lds_dwordx4 v[164:165], off
	s_add_i32 m0, s19, 0x4000
	v_lshl_add_u64 v[168:169], v[6:7], 0, v[0:1]
	global_load_lds_dwordx4 v[166:167], off
	s_add_i32 m0, s19, 0x6000
	v_lshl_add_u64 v[2:3], v[162:163], 0, 64
	global_load_lds_dwordx4 v[168:169], off
	s_add_i32 m0, s19, 0x8000
	s_add_i32 s22, s4, 0x2000
	global_load_lds_dwordx4 v[2:3], off
	v_lshl_add_u64 v[2:3], v[164:165], 0, 64
	s_add_i32 m0, s19, 0xa000
	v_lshrrev_b32_e32 v0, 2, v10
	global_load_lds_dwordx4 v[2:3], off
	v_lshl_add_u64 v[2:3], v[166:167], 0, 64
	s_add_i32 m0, s19, 0xc000
	v_bitop3_b32 v0, v170, v0, 3 bitop3:0x78
	global_load_lds_dwordx4 v[2:3], off
	v_lshl_add_u64 v[2:3], v[168:169], 0, 64
	s_add_i32 m0, s19, 0xe000
	s_or_b64 s[0:1], s[0:1], s[20:21]
	global_load_lds_dwordx4 v[2:3], off
	v_lshl_add_u64 v[2:3], v[162:163], 0, s[6:7]
	s_add_i32 m0, s8, s4
	v_and_b32_e32 v171, 15, v10
	global_load_lds_dwordx4 v[2:3], off
	v_lshl_add_u64 v[2:3], v[164:165], 0, s[6:7]
	s_add_i32 m0, s8, s22
	v_lshlrev_b32_e32 v172, 4, v0
	global_load_lds_dwordx4 v[2:3], off
	v_lshl_add_u64 v[2:3], v[166:167], 0, s[6:7]
	s_add_i32 m0, s9, s4
	v_mov_b32_e32 v0, v1
	global_load_lds_dwordx4 v[2:3], off
	v_lshl_add_u64 v[2:3], v[168:169], 0, s[6:7]
	s_add_i32 m0, s9, s22
	v_cndmask_b32_e64 v4, 0, 1, s[0:1]
	global_load_lds_dwordx4 v[2:3], off
	s_waitcnt vmcnt(8)
	v_mov_b32_e32 v2, v1
	v_mov_b32_e32 v3, v1
	s_waitcnt lgkmcnt(0)
	s_barrier
	v_mov_b64_e32 v[16:17], v[2:3]
	v_mov_b64_e32 v[24:25], v[2:3]
	v_mov_b64_e32 v[28:29], v[2:3]
	v_mov_b64_e32 v[32:33], v[2:3]
	v_mov_b64_e32 v[36:37], v[2:3]
	v_mov_b64_e32 v[40:41], v[2:3]
	v_mov_b64_e32 v[44:45], v[2:3]
	v_mov_b64_e32 v[48:49], v[2:3]
	v_mov_b64_e32 v[52:53], v[2:3]
	v_mov_b64_e32 v[56:57], v[2:3]
	v_mov_b64_e32 v[60:61], v[2:3]
	v_mov_b64_e32 v[64:65], v[2:3]
	v_mov_b64_e32 v[68:69], v[2:3]
	v_mov_b64_e32 v[72:73], v[2:3]
	v_mov_b64_e32 v[76:77], v[2:3]
	v_mov_b64_e32 v[80:81], v[2:3]
	v_mov_b64_e32 v[84:85], v[2:3]
	v_mov_b64_e32 v[88:89], v[2:3]
	v_mov_b64_e32 v[92:93], v[2:3]
	v_mov_b64_e32 v[96:97], v[2:3]
	v_mov_b64_e32 v[100:101], v[2:3]
	v_mov_b64_e32 v[104:105], v[2:3]
	v_mov_b64_e32 v[108:109], v[2:3]
	v_mov_b64_e32 v[112:113], v[2:3]
	v_mov_b64_e32 v[116:117], v[2:3]
	v_mov_b64_e32 v[120:121], v[2:3]
	v_mov_b64_e32 v[124:125], v[2:3]
	v_mov_b64_e32 v[128:129], v[2:3]
	v_mov_b64_e32 v[20:21], v[2:3]
	v_mov_b64_e32 v[12:13], v[2:3]
	v_mov_b64_e32 v[8:9], v[2:3]
	v_cmp_ne_u32_e64 s[0:1], 1, v4
	v_mov_b64_e32 v[14:15], v[0:1]
	v_mov_b64_e32 v[22:23], v[0:1]
	v_mov_b64_e32 v[26:27], v[0:1]
	v_mov_b64_e32 v[30:31], v[0:1]
	v_mov_b64_e32 v[34:35], v[0:1]
	v_mov_b64_e32 v[38:39], v[0:1]
	v_mov_b64_e32 v[42:43], v[0:1]
	v_mov_b64_e32 v[46:47], v[0:1]
	v_mov_b64_e32 v[50:51], v[0:1]
	v_mov_b64_e32 v[54:55], v[0:1]
	v_mov_b64_e32 v[58:59], v[0:1]
	v_mov_b64_e32 v[62:63], v[0:1]
	v_mov_b64_e32 v[66:67], v[0:1]
	v_mov_b64_e32 v[70:71], v[0:1]
	v_mov_b64_e32 v[74:75], v[0:1]
	v_mov_b64_e32 v[78:79], v[0:1]
	v_mov_b64_e32 v[82:83], v[0:1]
	v_mov_b64_e32 v[86:87], v[0:1]
	v_mov_b64_e32 v[90:91], v[0:1]
	v_mov_b64_e32 v[94:95], v[0:1]
	v_mov_b64_e32 v[98:99], v[0:1]
	v_mov_b64_e32 v[102:103], v[0:1]
	v_mov_b64_e32 v[106:107], v[0:1]
	v_mov_b64_e32 v[110:111], v[0:1]
	v_mov_b64_e32 v[114:115], v[0:1]
	v_mov_b64_e32 v[118:119], v[0:1]
	v_mov_b64_e32 v[122:123], v[0:1]
	v_mov_b64_e32 v[126:127], v[0:1]
	v_mov_b64_e32 v[18:19], v[0:1]
	v_mov_b64_e32 v[10:11], v[0:1]
	v_mov_b64_e32 v[6:7], v[0:1]
	v_mov_b64_e32 v[4:5], v[2:3]
	v_lshlrev_b32_e32 v173, 6, v171
	s_mov_b32 s20, s5
	s_movk_i32 s21, 0x60
	v_mov_b64_e32 v[2:3], v[0:1]
	s_mov_b32 s22, s5
	s_and_b32 s4, s20, 0x18000
	s_add_i32 s4, s4, 0
	s_add_i32 s23, s4, s18
	v_add3_u32 v0, s23, v173, v172
	s_add_i32 s4, s4, s17
	s_branch .LBB0_3007

.Lnd3_wd:
	s_add_i32 s22, s22, 1
	s_add_i32 s21, s21, 32
	s_add_i32 s20, s20, 0x8000
	s_and_b32 s4, s20, 0x18000
	s_add_i32 s4, s4, 0
	s_add_i32 s23, s4, s18
	v_add3_u32 v0, s23, v173, v172
	s_add_i32 s4, s4, s17
	s_cmpk_eq_i32 s21, 0x460
	s_waitcnt lgkmcnt(0)
	s_barrier
	s_cbranch_scc1 .LBB0_3009
.LBB0_3007:
	s_waitcnt lgkmcnt(0)
	ds_read_b128 v[130:133], v0 offset:16384
	ds_read_b128 v[134:137], v0 offset:17408
	ds_read_b128 v[138:141], v0 offset:18432
	ds_read_b128 v[142:145], v0 offset:19456
	v_add_u32_e32 v0, s4, v173
	s_add_i32 s4, s20, 0x18000
	s_and_b32 s23, s4, 0x18000
	s_cmp_lt_u32 s22, 29
	s_cselect_b32 s4, s21, 0x3e0
	s_lshl_b64 s[24:25], s[4:5], 1
	s_add_i32 s4, s19, s23
	v_add_u32_e32 v0, v0, v172
	ds_read_b128 v[154:157], v0
	ds_read_b128 v[150:153], v0 offset:1024
	ds_read_b128 v[146:149], v0 offset:2048
	s_and_b64 vcc, exec, s[0:1]
	s_cmp_lt_u32 s22, 29
	s_cbranch_scc0 .Lnd3_skip
	s_mov_b32 m0, s4
	v_lshl_add_u64 v[194:195], v[162:163], 0, s[24:25]
	global_load_lds_dwordx4 v[194:195], off
	s_add_i32 m0, s4, 0x2000
	v_lshl_add_u64 v[194:195], v[164:165], 0, s[24:25]
	global_load_lds_dwordx4 v[194:195], off
	s_add_i32 m0, s4, 0x4000
	v_lshl_add_u64 v[194:195], v[166:167], 0, s[24:25]
	global_load_lds_dwordx4 v[194:195], off
	s_add_i32 m0, s4, 0x6000
	v_lshl_add_u64 v[194:195], v[168:169], 0, s[24:25]
	global_load_lds_dwordx4 v[194:195], off

.LBB0_3086:
	s_and_b32 vcc_lo, s2, 7
	s_lshl_b32 vcc_lo, vcc_lo, 5
	s_lshr_b32 vcc_hi, s2, 3
	s_or_b32 vcc_lo, vcc_lo, vcc_hi
	s_cmpk_lt_i32 s2, 0x100
	s_cselect_b32 vcc_lo, vcc_lo, s2
	s_cmpk_lt_i32 s2, 0x100
	s_cselect_b64 s[10:11], -1, 0
	s_lshl_b32 s0, vcc_lo, 6
	s_and_b32 s0, s0, 0xffffff00
	s_lshl_b32 s1, vcc_lo, 8
	s_and_b32 s12, s1, 0x300
	s_add_i32 s1, s0, 0xffffc000
	s_cmpk_gt_i32 s2, 0xff
	s_cselect_b32 s21, 0x4000, s0
	s_cselect_b32 s0, s1, 0
	s_cselect_b32 s13, 8, 0x80
	s_ashr_i32 s1, s0, 31
	s_lshl_b64 s[0:1], s[0:1], 1
	s_add_u32 s22, s96, s0
	s_addc_u32 s23, s97, s1
	s_waitcnt vmcnt(1)
	v_mov_b32_e32 v10, v174
	s_add_u32 s0, s52, s0
	s_addc_u32 s1, s53, s1
	v_readfirstlane_b32 s6, v10
	s_ashr_i32 s24, s6, 6
	v_bfe_u32 v0, v10, 2, 4
	s_lshl_b32 s15, s24, 4
	v_or_b32_e32 v2, s21, v0
	s_add_i32 s25, s15, 0x80
	v_or_b32_e32 v0, s12, v0
	s_and_b32 s14, s24, 3
	v_add_u32_e32 v12, s15, v2
	v_add_u32_e32 v4, s25, v2
	v_mov_b64_e32 v[2:3], s[22:23]
	s_waitcnt vmcnt(0)
	v_add_u32_e32 v8, s15, v0
	v_mov_b64_e32 v[6:7], s[0:1]
	v_add_u32_e32 v0, s25, v0
	s_ashr_i32 s15, s6, 8
	v_bfe_u32 v166, v10, 4, 2
	v_mad_i64_i32 v[4:5], s[22:23], v4, s16, v[2:3]
	v_mad_i64_i32 v[8:9], s[0:1], v8, s16, v[6:7]
	v_mad_i64_i32 v[6:7], s[0:1], v0, s16, v[6:7]
	v_mad_i64_i32 v[2:3], s[0:1], v12, s16, v[2:3]
	s_cmp_lg_u32 s15, 1
	v_bitop3_b32 v11, v166, v10, 3 bitop3:0x78
	s_cselect_b64 s[0:1], -1, 0
	s_lshl_b32 s6, s24, 10
	v_lshlrev_b32_e32 v0, 4, v11
	s_add_i32 s22, s6, 0
	v_lshl_add_u64 v[158:159], v[2:3], 0, v[0:1]
	s_mov_b32 m0, s22
	v_lshl_add_u64 v[160:161], v[4:5], 0, v[0:1]
	global_load_lds_dwordx4 v[158:159], off
	s_add_i32 m0, s22, 0x2000
	v_lshl_add_u64 v[162:163], v[8:9], 0, v[0:1]
	global_load_lds_dwordx4 v[160:161], off
	s_add_i32 m0, s22, 0x4000
	v_lshl_add_u64 v[164:165], v[6:7], 0, v[0:1]
	global_load_lds_dwordx4 v[162:163], off
	s_add_i32 m0, s22, 0x6000
	v_lshl_add_u64 v[2:3], v[158:159], 0, 64
	global_load_lds_dwordx4 v[164:165], off
	s_add_i32 m0, s22, 0x8000
	s_add_i32 s23, s6, 0x2000
	global_load_lds_dwordx4 v[2:3], off
	v_lshl_add_u64 v[2:3], v[160:161], 0, 64
	s_add_i32 m0, s22, 0xa000
	v_lshrrev_b32_e32 v0, 2, v10
	global_load_lds_dwordx4 v[2:3], off
	v_lshl_add_u64 v[2:3], v[162:163], 0, 64
	s_add_i32 m0, s22, 0xc000
	v_bitop3_b32 v0, v166, v0, 3 bitop3:0x78
	global_load_lds_dwordx4 v[2:3], off
	v_lshl_add_u64 v[2:3], v[164:165], 0, 64
	s_add_i32 m0, s22, 0xe000
	s_or_b64 s[0:1], s[10:11], s[0:1]
	global_load_lds_dwordx4 v[2:3], off
	v_lshl_add_u64 v[2:3], v[158:159], 0, s[8:9]
	s_add_i32 m0, s18, s6
	v_and_b32_e32 v167, 15, v10
	global_load_lds_dwordx4 v[2:3], off
	v_lshl_add_u64 v[2:3], v[160:161], 0, s[8:9]
	s_add_i32 m0, s18, s23
	v_lshlrev_b32_e32 v169, 4, v0
	global_load_lds_dwordx4 v[2:3], off
	v_lshl_add_u64 v[2:3], v[162:163], 0, s[8:9]
	s_add_i32 m0, s19, s6
	v_mov_b32_e32 v0, v1
	global_load_lds_dwordx4 v[2:3], off
	v_lshl_add_u64 v[2:3], v[164:165], 0, s[8:9]
	s_add_i32 m0, s19, s23
	v_cndmask_b32_e64 v4, 0, 1, s[0:1]
	global_load_lds_dwordx4 v[2:3], off
	s_waitcnt vmcnt(8)
	v_mov_b32_e32 v2, v1
	v_mov_b32_e32 v3, v1
	s_waitcnt lgkmcnt(0)
	s_barrier
	v_mov_b64_e32 v[20:21], v[2:3]
	v_mov_b64_e32 v[24:25], v[2:3]
	v_mov_b64_e32 v[28:29], v[2:3]
	v_mov_b64_e32 v[32:33], v[2:3]
	v_mov_b64_e32 v[36:37], v[2:3]
	v_mov_b64_e32 v[40:41], v[2:3]
	v_mov_b64_e32 v[44:45], v[2:3]
	v_mov_b64_e32 v[48:49], v[2:3]
	v_mov_b64_e32 v[52:53], v[2:3]
	v_mov_b64_e32 v[56:57], v[2:3]
	v_mov_b64_e32 v[60:61], v[2:3]
	v_mov_b64_e32 v[64:65], v[2:3]
	v_mov_b64_e32 v[68:69], v[2:3]
	v_mov_b64_e32 v[72:73], v[2:3]
	v_mov_b64_e32 v[76:77], v[2:3]
	v_mov_b64_e32 v[80:81], v[2:3]
	v_mov_b64_e32 v[84:85], v[2:3]
	v_mov_b64_e32 v[88:89], v[2:3]
	v_mov_b64_e32 v[92:93], v[2:3]
	v_mov_b64_e32 v[96:97], v[2:3]
	v_mov_b64_e32 v[100:101], v[2:3]
	v_mov_b64_e32 v[104:105], v[2:3]
	v_mov_b64_e32 v[108:109], v[2:3]
	v_mov_b64_e32 v[112:113], v[2:3]
	v_mov_b64_e32 v[116:117], v[2:3]
	v_mov_b64_e32 v[120:121], v[2:3]
	v_mov_b64_e32 v[124:125], v[2:3]
	v_mov_b64_e32 v[128:129], v[2:3]
	v_mov_b64_e32 v[16:17], v[2:3]
	v_mov_b64_e32 v[12:13], v[2:3]
	v_mov_b64_e32 v[8:9], v[2:3]
	v_cmp_ne_u32_e64 s[0:1], 1, v4
	v_mov_b64_e32 v[18:19], v[0:1]
	v_mov_b64_e32 v[22:23], v[0:1]
	v_mov_b64_e32 v[26:27], v[0:1]
	v_mov_b64_e32 v[30:31], v[0:1]
	v_mov_b64_e32 v[34:35], v[0:1]
	v_mov_b64_e32 v[38:39], v[0:1]
	v_mov_b64_e32 v[42:43], v[0:1]
	v_mov_b64_e32 v[46:47], v[0:1]
	v_mov_b64_e32 v[50:51], v[0:1]
	v_mov_b64_e32 v[54:55], v[0:1]
	v_mov_b64_e32 v[58:59], v[0:1]
	v_mov_b64_e32 v[62:63], v[0:1]
	v_mov_b64_e32 v[66:67], v[0:1]
	v_mov_b64_e32 v[70:71], v[0:1]
	v_mov_b64_e32 v[74:75], v[0:1]
	v_mov_b64_e32 v[78:79], v[0:1]
	v_mov_b64_e32 v[82:83], v[0:1]
	v_mov_b64_e32 v[86:87], v[0:1]
	v_mov_b64_e32 v[90:91], v[0:1]
	v_mov_b64_e32 v[94:95], v[0:1]
	v_mov_b64_e32 v[98:99], v[0:1]
	v_mov_b64_e32 v[102:103], v[0:1]
	v_mov_b64_e32 v[106:107], v[0:1]
	v_mov_b64_e32 v[110:111], v[0:1]
	v_mov_b64_e32 v[114:115], v[0:1]
	v_mov_b64_e32 v[118:119], v[0:1]
	v_mov_b64_e32 v[122:123], v[0:1]
	v_mov_b64_e32 v[126:127], v[0:1]
	v_mov_b64_e32 v[14:15], v[0:1]
	v_mov_b64_e32 v[10:11], v[0:1]
	v_mov_b64_e32 v[6:7], v[0:1]
	v_mov_b64_e32 v[4:5], v[2:3]
	s_add_i32 s23, s13, -1
	s_lshl_b32 s24, s14, 12
	v_lshlrev_b32_e32 v168, 6, v167
	s_lshl_b32 s25, s15, 13
	s_mov_b32 s26, 0x18000
	v_mov_b64_e32 v[2:3], v[0:1]
	s_mov_b32 s27, s7
	s_add_i32 s6, s26, 0xfffe8000
	s_and_b32 s6, s6, 0x18000
	s_add_i32 s6, s6, 0
	s_add_i32 s28, s6, s24
	v_add3_u32 v0, s28, v168, v169
	s_add_i32 s6, s6, s25
	s_branch .LBB0_3088
.LBB0_3087:
	s_waitcnt vmcnt(8)
	s_add_i32 s27, s27, 1
	s_add_i32 s26, s26, 0x8000
	s_add_i32 s6, s26, 0xfffe8000
	s_and_b32 s6, s6, 0x18000
	s_add_i32 s6, s6, 0
	s_add_i32 s28, s6, s24
	v_add3_u32 v0, s28, v168, v169
	s_add_i32 s6, s6, s25
	s_cmp_eq_u32 s13, s27
	s_waitcnt lgkmcnt(0)
	s_barrier
	s_cbranch_scc1 .LBB0_3090
.LBB0_3088:
	s_waitcnt lgkmcnt(0)
	ds_read_b128 v[130:133], v0 offset:16384
	ds_read_b128 v[134:137], v0 offset:17408
	ds_read_b128 v[138:141], v0 offset:18432
	ds_read_b128 v[142:145], v0 offset:19456
	v_add_u32_e32 v0, s6, v168
	s_add_i32 s6, s27, 3
	s_min_u32 s6, s6, s23
	s_and_b32 s28, s26, 0x18000
	s_lshl_b32 s6, s6, 6
	s_add_i32 s28, s22, s28
	v_add_u32_e32 v0, v0, v169
	v_lshl_add_u64 v[170:171], v[158:159], 0, s[6:7]
	s_mov_b32 m0, s28
	ds_read_b128 v[154:157], v0
	ds_read_b128 v[150:153], v0 offset:1024
	ds_read_b128 v[146:149], v0 offset:2048
	global_load_lds_dwordx4 v[170:171], off
	v_lshl_add_u64 v[170:171], v[160:161], 0, s[6:7]
	s_add_i32 m0, s28, 0x2000
	s_and_b64 vcc, exec, s[0:1]
	global_load_lds_dwordx4 v[170:171], off
	v_lshl_add_u64 v[170:171], v[162:163], 0, s[6:7]
	s_add_i32 m0, s28, 0x4000
	s_nop 0
	global_load_lds_dwordx4 v[170:171], off
	v_lshl_add_u64 v[170:171], v[164:165], 0, s[6:7]
	s_add_i32 m0, s28, 0x6000
	s_nop 0
	global_load_lds_dwordx4 v[170:171], off
	s_cbranch_vccnz .LBB0_3087
	s_waitcnt lgkmcnt(0)
	v_mfma_f32_16x16x32_bf16 v[126:129], v[130:133], v[154:157], v[126:129]
	ds_read_b128 v[170:173], v0 offset:3072
	v_mfma_f32_16x16x32_bf16 v[122:125], v[134:137], v[154:157], v[122:125]
	v_mfma_f32_16x16x32_bf16 v[118:121], v[138:141], v[154:157], v[118:121]
	v_mfma_f32_16x16x32_bf16 v[114:117], v[142:145], v[154:157], v[114:117]
	v_mfma_f32_16x16x32_bf16 v[110:113], v[130:133], v[150:153], v[110:113]
	ds_read_b128 v[154:157], v0 offset:4096
	v_mfma_f32_16x16x32_bf16 v[106:109], v[134:137], v[150:153], v[106:109]
	v_mfma_f32_16x16x32_bf16 v[102:105], v[138:141], v[150:153], v[102:105]
	v_mfma_f32_16x16x32_bf16 v[98:101], v[142:145], v[150:153], v[98:101]
	v_mfma_f32_16x16x32_bf16 v[94:97], v[130:133], v[146:149], v[94:97]
	ds_read_b128 v[150:153], v0 offset:5120
	v_mfma_f32_16x16x32_bf16 v[90:93], v[134:137], v[146:149], v[90:93]
	v_mfma_f32_16x16x32_bf16 v[86:89], v[138:141], v[146:149], v[86:89]
	v_mfma_f32_16x16x32_bf16 v[82:85], v[142:145], v[146:149], v[82:85]
	s_waitcnt lgkmcnt(0)
	v_mfma_f32_16x16x32_bf16 v[78:81], v[130:133], v[170:173], v[78:81]
	ds_read_b128 v[146:149], v0 offset:6144
	v_mfma_f32_16x16x32_bf16 v[74:77], v[134:137], v[170:173], v[74:77]
	v_mfma_f32_16x16x32_bf16 v[70:73], v[138:141], v[170:173], v[70:73]
	v_mfma_f32_16x16x32_bf16 v[66:69], v[142:145], v[170:173], v[66:69]
	v_mfma_f32_16x16x32_bf16 v[62:65], v[130:133], v[154:157], v[62:65]
	ds_read_b128 v[170:173], v0 offset:7168
	v_mfma_f32_16x16x32_bf16 v[58:61], v[134:137], v[154:157], v[58:61]
	v_mfma_f32_16x16x32_bf16 v[54:57], v[138:141], v[154:157], v[54:57]
	v_mfma_f32_16x16x32_bf16 v[50:53], v[142:145], v[154:157], v[50:53]
	v_mfma_f32_16x16x32_bf16 v[46:49], v[130:133], v[150:153], v[46:49]
	v_mfma_f32_16x16x32_bf16 v[42:45], v[134:137], v[150:153], v[42:45]
	v_mfma_f32_16x16x32_bf16 v[38:41], v[138:141], v[150:153], v[38:41]
	v_mfma_f32_16x16x32_bf16 v[34:37], v[142:145], v[150:153], v[34:37]
	s_waitcnt lgkmcnt(0)
	v_mfma_f32_16x16x32_bf16 v[30:33], v[130:133], v[146:149], v[30:33]
	v_mfma_f32_16x16x32_bf16 v[26:29], v[134:137], v[146:149], v[26:29]
	v_mfma_f32_16x16x32_bf16 v[22:25], v[138:141], v[146:149], v[22:25]
	v_mfma_f32_16x16x32_bf16 v[18:21], v[142:145], v[146:149], v[18:21]
	v_mfma_f32_16x16x32_bf16 v[14:17], v[130:133], v[170:173], v[14:17]
	v_mfma_f32_16x16x32_bf16 v[10:13], v[134:137], v[170:173], v[10:13]
	v_mfma_f32_16x16x32_bf16 v[6:9], v[138:141], v[170:173], v[6:9]
	v_mfma_f32_16x16x32_bf16 v[2:5], v[142:145], v[170:173], v[2:5]
	s_branch .LBB0_3087
